# layer 0: next layer's pre-norm also fused into the w_out epilogue (second row-sum exchange on the new rows, bf16 column pairs assembled across lane pairs), post phase of layer 0 reduced to the context
# speedup vs baseline: 1.0191x; 1.0125x over previous
.Lgo_fz_epi:
	s_nop 7
	s_nop 7
	s_load_dwordx2 s[94:95], s[88:89], 0x168
	s_load_dwordx2 s[98:99], s[88:89], 0x170
	s_load_dwordx2 s[2:3], s[88:89], 0xc0
	v_and_b32_e32 v160, 15, v167
	v_bfe_u32 v161, v167, 4, 2
	v_bfe_u32 v162, v167, 6, 2
	v_lshrrev_b32_e32 v163, 8, v167
	v_lshlrev_b32_e32 v163, 6, v163
	v_lshl_add_u32 v163, v161, 2, v163
	v_lshl_add_u32 v164, v162, 5, v160
	v_readlane_b32 s32, v255, 0
	s_lshr_b32 s45, s36, 8
	s_lshl_b32 s48, s45, 3
	s_lshr_b32 s57, s34, 8
	s_add_u32 s48, s48, s57
	s_lshl_b32 s48, s48, 10
	s_lshr_b32 s57, s36, 12
	s_mul_i32 s0, s32, 5
	s_add_u32 s57, s57, s0
	s_mul_i32 s57, s57, 0x6000
	s_add_u32 s57, s57, 0x4000
	v_lshlrev_b32_e32 v237, 2, v164
	s_lshl_b32 vcc_lo, s34, 2
	v_add_u32_e32 v237, vcc_lo, v237
	v_add_u32_e32 v168, s36, v163
	v_lshlrev_b32_e32 v168, 13, v168
	v_add_u32_e32 v168, v168, v237
	v_add_u32_e32 v169, 0x2000, v168
	v_add_u32_e32 v170, 0x4000, v168
	v_add_u32_e32 v171, 0x6000, v168
	s_lshl_b32 s0, s45, 2
	s_add_u32 s0, s0, 0x204
	v_mov_b32_e32 v234, s0
	s_lshl_b32 s0, s45, 13
	v_lshl_add_u32 v235, v167, 2, s0
	s_lshl_b32 s45, s32, 4
	s_add_u32 s45, s45, 8
	s_load_dwordx2 s[36:37], s[88:89], 0xc8
	s_load_dwordx2 s[34:35], s[88:89], 0xf0
	s_load_dwordx2 s[0:1], s[88:89], 0x0
	v_mul_f32_e32 v194, v124, v124
	v_fmac_f32_e32 v194, v120, v120
	v_fmac_f32_e32 v194, v100, v100
	v_fmac_f32_e32 v194, v96, v96
	v_mul_f32_e32 v195, v125, v125
	v_fmac_f32_e32 v195, v121, v121
	v_fmac_f32_e32 v195, v101, v101
	v_fmac_f32_e32 v195, v97, v97
	v_mul_f32_e32 v196, v126, v126
	v_fmac_f32_e32 v196, v122, v122
	v_fmac_f32_e32 v196, v102, v102
	v_fmac_f32_e32 v196, v98, v98
	v_mul_f32_e32 v197, v127, v127
	v_fmac_f32_e32 v197, v123, v123
	v_fmac_f32_e32 v197, v103, v103
	v_fmac_f32_e32 v197, v99, v99
	v_mul_f32_e32 v198, v116, v116
	v_fmac_f32_e32 v198, v112, v112
	v_fmac_f32_e32 v198, v92, v92
	v_fmac_f32_e32 v198, v88, v88
	v_mul_f32_e32 v199, v117, v117
	v_fmac_f32_e32 v199, v113, v113
	v_fmac_f32_e32 v199, v93, v93
	v_fmac_f32_e32 v199, v89, v89
	v_mul_f32_e32 v200, v118, v118
	v_fmac_f32_e32 v200, v114, v114
	v_fmac_f32_e32 v200, v94, v94
	v_fmac_f32_e32 v200, v90, v90
	v_mul_f32_e32 v201, v119, v119
	v_fmac_f32_e32 v201, v115, v115
	v_fmac_f32_e32 v201, v95, v95
	v_fmac_f32_e32 v201, v91, v91
	v_mul_f32_e32 v202, v108, v108
	v_fmac_f32_e32 v202, v104, v104
	v_fmac_f32_e32 v202, v80, v80
	v_fmac_f32_e32 v202, v72, v72
	v_mul_f32_e32 v203, v109, v109
	v_fmac_f32_e32 v203, v105, v105
	v_fmac_f32_e32 v203, v81, v81
	v_fmac_f32_e32 v203, v73, v73
	v_mul_f32_e32 v204, v110, v110
	v_fmac_f32_e32 v204, v106, v106
	v_fmac_f32_e32 v204, v82, v82
	v_fmac_f32_e32 v204, v74, v74
	v_mul_f32_e32 v205, v111, v111
	v_fmac_f32_e32 v205, v107, v107
	v_fmac_f32_e32 v205, v83, v83
	v_fmac_f32_e32 v205, v75, v75
	v_mul_f32_e32 v206, v84, v84
	v_fmac_f32_e32 v206, v76, v76
	v_fmac_f32_e32 v206, v68, v68
	v_fmac_f32_e32 v206, v64, v64
	v_mul_f32_e32 v207, v85, v85
	v_fmac_f32_e32 v207, v77, v77
	v_fmac_f32_e32 v207, v69, v69
	v_fmac_f32_e32 v207, v65, v65
	v_mul_f32_e32 v208, v86, v86
	v_fmac_f32_e32 v208, v78, v78
	v_fmac_f32_e32 v208, v70, v70
	v_fmac_f32_e32 v208, v66, v66
	v_mul_f32_e32 v209, v87, v87
	v_fmac_f32_e32 v209, v79, v79
	v_fmac_f32_e32 v209, v71, v71
	v_fmac_f32_e32 v209, v67, v67
	v_mul_f32_e32 v210, v60, v60
	v_fmac_f32_e32 v210, v56, v56
	v_fmac_f32_e32 v210, v32, v32
	v_fmac_f32_e32 v210, v24, v24
	v_mul_f32_e32 v211, v61, v61
	v_fmac_f32_e32 v211, v57, v57
	v_fmac_f32_e32 v211, v33, v33
	v_fmac_f32_e32 v211, v25, v25
	v_mul_f32_e32 v212, v62, v62
	v_fmac_f32_e32 v212, v58, v58
	v_fmac_f32_e32 v212, v34, v34
	v_fmac_f32_e32 v212, v26, v26
	v_mul_f32_e32 v213, v63, v63
	v_fmac_f32_e32 v213, v59, v59
	v_fmac_f32_e32 v213, v35, v35
	v_fmac_f32_e32 v213, v27, v27
	v_mul_f32_e32 v214, v52, v52
	v_fmac_f32_e32 v214, v48, v48
	v_fmac_f32_e32 v214, v20, v20
	v_fmac_f32_e32 v214, v16, v16
	v_mul_f32_e32 v215, v53, v53
	v_fmac_f32_e32 v215, v49, v49
	v_fmac_f32_e32 v215, v21, v21
	v_fmac_f32_e32 v215, v17, v17
	v_mul_f32_e32 v216, v54, v54
	v_fmac_f32_e32 v216, v50, v50
	v_fmac_f32_e32 v216, v22, v22
	v_fmac_f32_e32 v216, v18, v18
	v_mul_f32_e32 v217, v55, v55
	v_fmac_f32_e32 v217, v51, v51
	v_fmac_f32_e32 v217, v23, v23
	v_fmac_f32_e32 v217, v19, v19
	v_mul_f32_e32 v218, v44, v44
	v_fmac_f32_e32 v218, v40, v40
	v_fmac_f32_e32 v218, v12, v12
	v_fmac_f32_e32 v218, v8, v8
	v_mul_f32_e32 v219, v45, v45
	v_fmac_f32_e32 v219, v41, v41
	v_fmac_f32_e32 v219, v13, v13
	v_fmac_f32_e32 v219, v9, v9
	v_mul_f32_e32 v220, v46, v46
	v_fmac_f32_e32 v220, v42, v42
	v_fmac_f32_e32 v220, v14, v14
	v_fmac_f32_e32 v220, v10, v10
	v_mul_f32_e32 v221, v47, v47
	v_fmac_f32_e32 v221, v43, v43
	v_fmac_f32_e32 v221, v15, v15
	v_fmac_f32_e32 v221, v11, v11
	v_mul_f32_e32 v222, v36, v36
	v_fmac_f32_e32 v222, v28, v28
	v_fmac_f32_e32 v222, v4, v4
	v_fmac_f32_e32 v222, v0, v0
	v_mul_f32_e32 v223, v37, v37
	v_fmac_f32_e32 v223, v29, v29
	v_fmac_f32_e32 v223, v5, v5
	v_fmac_f32_e32 v223, v1, v1
	v_mul_f32_e32 v224, v38, v38
	v_fmac_f32_e32 v224, v30, v30
	v_fmac_f32_e32 v224, v6, v6
	v_fmac_f32_e32 v224, v2, v2
	v_mul_f32_e32 v225, v39, v39
	v_fmac_f32_e32 v225, v31, v31
	v_fmac_f32_e32 v225, v7, v7
	v_fmac_f32_e32 v225, v3, v3
	s_nop 1
	v_add_f32_dpp v194, v194, v194 row_ror:8 row_mask:0xf bank_mask:0xf
	v_add_f32_dpp v195, v195, v195 row_ror:8 row_mask:0xf bank_mask:0xf
	v_add_f32_dpp v196, v196, v196 row_ror:8 row_mask:0xf bank_mask:0xf
	v_add_f32_dpp v197, v197, v197 row_ror:8 row_mask:0xf bank_mask:0xf
	v_add_f32_dpp v198, v198, v198 row_ror:8 row_mask:0xf bank_mask:0xf
	v_add_f32_dpp v199, v199, v199 row_ror:8 row_mask:0xf bank_mask:0xf
	v_add_f32_dpp v200, v200, v200 row_ror:8 row_mask:0xf bank_mask:0xf
	v_add_f32_dpp v201, v201, v201 row_ror:8 row_mask:0xf bank_mask:0xf
	v_add_f32_dpp v202, v202, v202 row_ror:8 row_mask:0xf bank_mask:0xf
	v_add_f32_dpp v203, v203, v203 row_ror:8 row_mask:0xf bank_mask:0xf
	v_add_f32_dpp v204, v204, v204 row_ror:8 row_mask:0xf bank_mask:0xf
	v_add_f32_dpp v205, v205, v205 row_ror:8 row_mask:0xf bank_mask:0xf
	v_add_f32_dpp v206, v206, v206 row_ror:8 row_mask:0xf bank_mask:0xf
	v_add_f32_dpp v207, v207, v207 row_ror:8 row_mask:0xf bank_mask:0xf
	v_add_f32_dpp v208, v208, v208 row_ror:8 row_mask:0xf bank_mask:0xf
	v_add_f32_dpp v209, v209, v209 row_ror:8 row_mask:0xf bank_mask:0xf
	v_add_f32_dpp v210, v210, v210 row_ror:8 row_mask:0xf bank_mask:0xf
	v_add_f32_dpp v211, v211, v211 row_ror:8 row_mask:0xf bank_mask:0xf
	v_add_f32_dpp v212, v212, v212 row_ror:8 row_mask:0xf bank_mask:0xf
	v_add_f32_dpp v213, v213, v213 row_ror:8 row_mask:0xf bank_mask:0xf
	v_add_f32_dpp v214, v214, v214 row_ror:8 row_mask:0xf bank_mask:0xf
	v_add_f32_dpp v215, v215, v215 row_ror:8 row_mask:0xf bank_mask:0xf
	v_add_f32_dpp v216, v216, v216 row_ror:8 row_mask:0xf bank_mask:0xf
	v_add_f32_dpp v217, v217, v217 row_ror:8 row_mask:0xf bank_mask:0xf
	v_add_f32_dpp v218, v218, v218 row_ror:8 row_mask:0xf bank_mask:0xf
	v_add_f32_dpp v219, v219, v219 row_ror:8 row_mask:0xf bank_mask:0xf
	v_add_f32_dpp v220, v220, v220 row_ror:8 row_mask:0xf bank_mask:0xf
	v_add_f32_dpp v221, v221, v221 row_ror:8 row_mask:0xf bank_mask:0xf
	v_add_f32_dpp v222, v222, v222 row_ror:8 row_mask:0xf bank_mask:0xf
	v_add_f32_dpp v223, v223, v223 row_ror:8 row_mask:0xf bank_mask:0xf
	v_add_f32_dpp v224, v224, v224 row_ror:8 row_mask:0xf bank_mask:0xf
	v_add_f32_dpp v225, v225, v225 row_ror:8 row_mask:0xf bank_mask:0xf
	s_nop 1
	v_add_f32_dpp v194, v194, v194 row_ror:4 row_mask:0xf bank_mask:0xf
	v_add_f32_dpp v195, v195, v195 row_ror:4 row_mask:0xf bank_mask:0xf
	v_add_f32_dpp v196, v196, v196 row_ror:4 row_mask:0xf bank_mask:0xf
	v_add_f32_dpp v197, v197, v197 row_ror:4 row_mask:0xf bank_mask:0xf
	v_add_f32_dpp v198, v198, v198 row_ror:4 row_mask:0xf bank_mask:0xf
	v_add_f32_dpp v199, v199, v199 row_ror:4 row_mask:0xf bank_mask:0xf
	v_add_f32_dpp v200, v200, v200 row_ror:4 row_mask:0xf bank_mask:0xf
	v_add_f32_dpp v201, v201, v201 row_ror:4 row_mask:0xf bank_mask:0xf
	v_add_f32_dpp v202, v202, v202 row_ror:4 row_mask:0xf bank_mask:0xf
	v_add_f32_dpp v203, v203, v203 row_ror:4 row_mask:0xf bank_mask:0xf
	v_add_f32_dpp v204, v204, v204 row_ror:4 row_mask:0xf bank_mask:0xf
	v_add_f32_dpp v205, v205, v205 row_ror:4 row_mask:0xf bank_mask:0xf
	v_add_f32_dpp v206, v206, v206 row_ror:4 row_mask:0xf bank_mask:0xf
	v_add_f32_dpp v207, v207, v207 row_ror:4 row_mask:0xf bank_mask:0xf
	v_add_f32_dpp v208, v208, v208 row_ror:4 row_mask:0xf bank_mask:0xf
	v_add_f32_dpp v209, v209, v209 row_ror:4 row_mask:0xf bank_mask:0xf
	v_add_f32_dpp v210, v210, v210 row_ror:4 row_mask:0xf bank_mask:0xf
	v_add_f32_dpp v211, v211, v211 row_ror:4 row_mask:0xf bank_mask:0xf
	v_add_f32_dpp v212, v212, v212 row_ror:4 row_mask:0xf bank_mask:0xf
	v_add_f32_dpp v213, v213, v213 row_ror:4 row_mask:0xf bank_mask:0xf
	v_add_f32_dpp v214, v214, v214 row_ror:4 row_mask:0xf bank_mask:0xf
	v_add_f32_dpp v215, v215, v215 row_ror:4 row_mask:0xf bank_mask:0xf
	v_add_f32_dpp v216, v216, v216 row_ror:4 row_mask:0xf bank_mask:0xf
	v_add_f32_dpp v217, v217, v217 row_ror:4 row_mask:0xf bank_mask:0xf
	v_add_f32_dpp v218, v218, v218 row_ror:4 row_mask:0xf bank_mask:0xf
	v_add_f32_dpp v219, v219, v219 row_ror:4 row_mask:0xf bank_mask:0xf
	v_add_f32_dpp v220, v220, v220 row_ror:4 row_mask:0xf bank_mask:0xf
	v_add_f32_dpp v221, v221, v221 row_ror:4 row_mask:0xf bank_mask:0xf
	v_add_f32_dpp v222, v222, v222 row_ror:4 row_mask:0xf bank_mask:0xf
	v_add_f32_dpp v223, v223, v223 row_ror:4 row_mask:0xf bank_mask:0xf
	v_add_f32_dpp v224, v224, v224 row_ror:4 row_mask:0xf bank_mask:0xf
	v_add_f32_dpp v225, v225, v225 row_ror:4 row_mask:0xf bank_mask:0xf
	s_nop 1
	v_add_f32_dpp v194, v194, v194 row_ror:2 row_mask:0xf bank_mask:0xf
	v_add_f32_dpp v195, v195, v195 row_ror:2 row_mask:0xf bank_mask:0xf
	v_add_f32_dpp v196, v196, v196 row_ror:2 row_mask:0xf bank_mask:0xf
	v_add_f32_dpp v197, v197, v197 row_ror:2 row_mask:0xf bank_mask:0xf
	v_add_f32_dpp v198, v198, v198 row_ror:2 row_mask:0xf bank_mask:0xf
	v_add_f32_dpp v199, v199, v199 row_ror:2 row_mask:0xf bank_mask:0xf
	v_add_f32_dpp v200, v200, v200 row_ror:2 row_mask:0xf bank_mask:0xf
	v_add_f32_dpp v201, v201, v201 row_ror:2 row_mask:0xf bank_mask:0xf
	v_add_f32_dpp v202, v202, v202 row_ror:2 row_mask:0xf bank_mask:0xf
	v_add_f32_dpp v203, v203, v203 row_ror:2 row_mask:0xf bank_mask:0xf
	v_add_f32_dpp v204, v204, v204 row_ror:2 row_mask:0xf bank_mask:0xf
	v_add_f32_dpp v205, v205, v205 row_ror:2 row_mask:0xf bank_mask:0xf
	v_add_f32_dpp v206, v206, v206 row_ror:2 row_mask:0xf bank_mask:0xf
	v_add_f32_dpp v207, v207, v207 row_ror:2 row_mask:0xf bank_mask:0xf
	v_add_f32_dpp v208, v208, v208 row_ror:2 row_mask:0xf bank_mask:0xf
	v_add_f32_dpp v209, v209, v209 row_ror:2 row_mask:0xf bank_mask:0xf
	v_add_f32_dpp v210, v210, v210 row_ror:2 row_mask:0xf bank_mask:0xf
	v_add_f32_dpp v211, v211, v211 row_ror:2 row_mask:0xf bank_mask:0xf
	v_add_f32_dpp v212, v212, v212 row_ror:2 row_mask:0xf bank_mask:0xf
	v_add_f32_dpp v213, v213, v213 row_ror:2 row_mask:0xf bank_mask:0xf
	v_add_f32_dpp v214, v214, v214 row_ror:2 row_mask:0xf bank_mask:0xf
	v_add_f32_dpp v215, v215, v215 row_ror:2 row_mask:0xf bank_mask:0xf
	v_add_f32_dpp v216, v216, v216 row_ror:2 row_mask:0xf bank_mask:0xf
	v_add_f32_dpp v217, v217, v217 row_ror:2 row_mask:0xf bank_mask:0xf
	v_add_f32_dpp v218, v218, v218 row_ror:2 row_mask:0xf bank_mask:0xf
	v_add_f32_dpp v219, v219, v219 row_ror:2 row_mask:0xf bank_mask:0xf
	v_add_f32_dpp v220, v220, v220 row_ror:2 row_mask:0xf bank_mask:0xf
	v_add_f32_dpp v221, v221, v221 row_ror:2 row_mask:0xf bank_mask:0xf
	v_add_f32_dpp v222, v222, v222 row_ror:2 row_mask:0xf bank_mask:0xf
	v_add_f32_dpp v223, v223, v223 row_ror:2 row_mask:0xf bank_mask:0xf
	v_add_f32_dpp v224, v224, v224 row_ror:2 row_mask:0xf bank_mask:0xf
	v_add_f32_dpp v225, v225, v225 row_ror:2 row_mask:0xf bank_mask:0xf
	s_nop 1
	v_add_f32_dpp v194, v194, v194 row_ror:1 row_mask:0xf bank_mask:0xf
	v_add_f32_dpp v195, v195, v195 row_ror:1 row_mask:0xf bank_mask:0xf
	v_add_f32_dpp v196, v196, v196 row_ror:1 row_mask:0xf bank_mask:0xf
	v_add_f32_dpp v197, v197, v197 row_ror:1 row_mask:0xf bank_mask:0xf
	v_add_f32_dpp v198, v198, v198 row_ror:1 row_mask:0xf bank_mask:0xf
	v_add_f32_dpp v199, v199, v199 row_ror:1 row_mask:0xf bank_mask:0xf
	v_add_f32_dpp v200, v200, v200 row_ror:1 row_mask:0xf bank_mask:0xf
	v_add_f32_dpp v201, v201, v201 row_ror:1 row_mask:0xf bank_mask:0xf
	v_add_f32_dpp v202, v202, v202 row_ror:1 row_mask:0xf bank_mask:0xf
	v_add_f32_dpp v203, v203, v203 row_ror:1 row_mask:0xf bank_mask:0xf
	v_add_f32_dpp v204, v204, v204 row_ror:1 row_mask:0xf bank_mask:0xf
	v_add_f32_dpp v205, v205, v205 row_ror:1 row_mask:0xf bank_mask:0xf
	v_add_f32_dpp v206, v206, v206 row_ror:1 row_mask:0xf bank_mask:0xf
	v_add_f32_dpp v207, v207, v207 row_ror:1 row_mask:0xf bank_mask:0xf
	v_add_f32_dpp v208, v208, v208 row_ror:1 row_mask:0xf bank_mask:0xf
	v_add_f32_dpp v209, v209, v209 row_ror:1 row_mask:0xf bank_mask:0xf
	v_add_f32_dpp v210, v210, v210 row_ror:1 row_mask:0xf bank_mask:0xf
	v_add_f32_dpp v211, v211, v211 row_ror:1 row_mask:0xf bank_mask:0xf
	v_add_f32_dpp v212, v212, v212 row_ror:1 row_mask:0xf bank_mask:0xf
	v_add_f32_dpp v213, v213, v213 row_ror:1 row_mask:0xf bank_mask:0xf
	v_add_f32_dpp v214, v214, v214 row_ror:1 row_mask:0xf bank_mask:0xf
	v_add_f32_dpp v215, v215, v215 row_ror:1 row_mask:0xf bank_mask:0xf
	v_add_f32_dpp v216, v216, v216 row_ror:1 row_mask:0xf bank_mask:0xf
	v_add_f32_dpp v217, v217, v217 row_ror:1 row_mask:0xf bank_mask:0xf
	v_add_f32_dpp v218, v218, v218 row_ror:1 row_mask:0xf bank_mask:0xf
	v_add_f32_dpp v219, v219, v219 row_ror:1 row_mask:0xf bank_mask:0xf
	v_add_f32_dpp v220, v220, v220 row_ror:1 row_mask:0xf bank_mask:0xf
	v_add_f32_dpp v221, v221, v221 row_ror:1 row_mask:0xf bank_mask:0xf
	v_add_f32_dpp v222, v222, v222 row_ror:1 row_mask:0xf bank_mask:0xf
	v_add_f32_dpp v223, v223, v223 row_ror:1 row_mask:0xf bank_mask:0xf
	v_add_f32_dpp v224, v224, v224 row_ror:1 row_mask:0xf bank_mask:0xf
	v_add_f32_dpp v225, v225, v225 row_ror:1 row_mask:0xf bank_mask:0xf
	v_lshlrev_b32_e32 v236, 10, v162
	v_lshl_add_u32 v236, v163, 2, v236
	v_add_u32_e32 v236, 0x20000, v236
	v_cmp_eq_u32_e32 vcc, 0, v160
	s_mov_b64 exec, vcc
	ds_write_b128 v236, v[194:197]
	ds_write_b128 v236, v[198:201] offset:64
	ds_write_b128 v236, v[202:205] offset:128
	ds_write_b128 v236, v[206:209] offset:192
	ds_write_b128 v236, v[210:213] offset:512
	ds_write_b128 v236, v[214:217] offset:576
	ds_write_b128 v236, v[218:221] offset:640
	ds_write_b128 v236, v[222:225] offset:704
	s_mov_b64 exec, -1
	s_waitcnt lgkmcnt(0)
	s_add_u32 s34, s34, s57
	s_addc_u32 s35, s35, 0
	s_lshl_b32 s57, s32, 13
	s_add_u32 s2, s2, s57
	s_addc_u32 s3, s3, 0
	s_cmp_eq_u32 s32, 0
	s_cselect_b32 s0, s0, s36
	s_cselect_b32 s1, s1, s37
	s_add_u32 s94, s94, 0x1000000
	s_addc_u32 s95, s95, 0
	v_readfirstlane_b32 s32, v167
	s_barrier
	s_cmp_lt_u32 s32, 0x100
	s_cbranch_scc0 .Lgo_fz_w1
	v_lshlrev_b32_e32 v238, 2, v167
	v_add_u32_e32 v239, 0x20000, v238
	ds_read_b32 v240, v239
	ds_read_b32 v241, v239 offset:1024
	ds_read_b32 v242, v239 offset:2048
	ds_read_b32 v243, v239 offset:3072
	v_add_u32_e32 v244, s48, v238
	s_waitcnt lgkmcnt(0)
	v_add_f32_e32 v240, v240, v241
	v_add_f32_e32 v240, v240, v242
	v_add_f32_e32 v240, v240, v243
	global_store_dword v244, v240, s[94:95] sc0 sc1
	s_waitcnt vmcnt(0)

.Lgo_fz_w3:
	s_barrier
	v_lshlrev_b32_e32 v236, 2, v163
	v_add_u32_e32 v236, 0x20000, v236
	ds_read_b128 v[194:197], v236
	ds_read_b128 v[198:201], v236 offset:64
	ds_read_b128 v[202:205], v236 offset:128
	ds_read_b128 v[206:209], v236 offset:192
	ds_read_b128 v[210:213], v236 offset:512
	ds_read_b128 v[214:217], v236 offset:576
	ds_read_b128 v[218:221], v236 offset:640
	ds_read_b128 v[222:225], v236 offset:704
	s_waitcnt lgkmcnt(0)
	s_waitcnt vmcnt(16)
	v_mul_f32_e32 v124, v124, v226
	v_mul_f32_e32 v124, v124, v194
	v_fma_f32 v124, v124, v230, v128
	v_mul_f32_e32 v125, v125, v226
	v_mul_f32_e32 v125, v125, v195
	v_fma_f32 v125, v125, v230, v129
	v_mul_f32_e32 v126, v126, v226
	v_mul_f32_e32 v126, v126, v196
	v_fma_f32 v126, v126, v230, v130
	v_mul_f32_e32 v127, v127, v226
	v_mul_f32_e32 v127, v127, v197
	v_fma_f32 v127, v127, v230, v131
	v_mul_f32_e32 v120, v120, v227
	v_mul_f32_e32 v120, v120, v194
	v_fma_f32 v120, v120, v231, v132
	v_mul_f32_e32 v121, v121, v227
	v_mul_f32_e32 v121, v121, v195
	v_fma_f32 v121, v121, v231, v133
	v_mul_f32_e32 v122, v122, v227
	v_mul_f32_e32 v122, v122, v196
	v_fma_f32 v122, v122, v231, v134
	v_mul_f32_e32 v123, v123, v227
	v_mul_f32_e32 v123, v123, v197
	v_fma_f32 v123, v123, v231, v135
	v_mul_f32_e32 v100, v100, v228
	v_mul_f32_e32 v100, v100, v194
	v_fma_f32 v100, v100, v232, v136
	v_mul_f32_e32 v101, v101, v228
	v_mul_f32_e32 v101, v101, v195
	v_fma_f32 v101, v101, v232, v137
	v_mul_f32_e32 v102, v102, v228
	v_mul_f32_e32 v102, v102, v196
	v_fma_f32 v102, v102, v232, v138
	v_mul_f32_e32 v103, v103, v228
	v_mul_f32_e32 v103, v103, v197
	v_fma_f32 v103, v103, v232, v139
	v_mul_f32_e32 v96, v96, v229
	v_mul_f32_e32 v96, v96, v194
	v_fma_f32 v96, v96, v233, v140
	v_mul_f32_e32 v97, v97, v229
	v_mul_f32_e32 v97, v97, v195
	v_fma_f32 v97, v97, v233, v141
	v_mul_f32_e32 v98, v98, v229
	v_mul_f32_e32 v98, v98, v196
	v_fma_f32 v98, v98, v233, v142
	v_mul_f32_e32 v99, v99, v229
	v_mul_f32_e32 v99, v99, v197
	v_fma_f32 v99, v99, v233, v143
	global_store_dword v172, v124, s[36:37]
	global_store_dword v173, v125, s[36:37]
	global_store_dword v174, v126, s[36:37]
	global_store_dword v175, v127, s[36:37]
	global_store_dword v172, v120, s[36:37] offset:64
	global_store_dword v173, v121, s[36:37] offset:64
	global_store_dword v174, v122, s[36:37] offset:64
	global_store_dword v175, v123, s[36:37] offset:64
	global_store_dword v172, v100, s[36:37] offset:512
	global_store_dword v173, v101, s[36:37] offset:512
	global_store_dword v174, v102, s[36:37] offset:512
	global_store_dword v175, v103, s[36:37] offset:512
	global_store_dword v172, v96, s[36:37] offset:576
	global_store_dword v173, v97, s[36:37] offset:576
	global_store_dword v174, v98, s[36:37] offset:576
	global_store_dword v175, v99, s[36:37] offset:576
	v_add_u32_e32 v172, 0x40000, v168
	v_add_u32_e32 v173, 0x40000, v169
	v_add_u32_e32 v174, 0x40000, v170
	v_add_u32_e32 v175, 0x40000, v171
	global_load_dword v128, v172, s[0:1]
	global_load_dword v129, v173, s[0:1]
	global_load_dword v130, v174, s[0:1]
	global_load_dword v131, v175, s[0:1]
	global_load_dword v132, v172, s[0:1] offset:64
	global_load_dword v133, v173, s[0:1] offset:64
	global_load_dword v134, v174, s[0:1] offset:64
	global_load_dword v135, v175, s[0:1] offset:64
	global_load_dword v136, v172, s[0:1] offset:512
	global_load_dword v137, v173, s[0:1] offset:512
	global_load_dword v138, v174, s[0:1] offset:512
	global_load_dword v139, v175, s[0:1] offset:512
	global_load_dword v140, v172, s[0:1] offset:576
	global_load_dword v141, v173, s[0:1] offset:576
	global_load_dword v142, v174, s[0:1] offset:576
	global_load_dword v143, v175, s[0:1] offset:576
	s_waitcnt vmcnt(32)
	v_mul_f32_e32 v116, v116, v226
	v_mul_f32_e32 v116, v116, v198
	v_fma_f32 v116, v116, v230, v144
	v_mul_f32_e32 v117, v117, v226
	v_mul_f32_e32 v117, v117, v199
	v_fma_f32 v117, v117, v230, v145
	v_mul_f32_e32 v118, v118, v226
	v_mul_f32_e32 v118, v118, v200
	v_fma_f32 v118, v118, v230, v146
	v_mul_f32_e32 v119, v119, v226
	v_mul_f32_e32 v119, v119, v201
	v_fma_f32 v119, v119, v230, v147
	v_mul_f32_e32 v112, v112, v227
	v_mul_f32_e32 v112, v112, v198
	v_fma_f32 v112, v112, v231, v148
	v_mul_f32_e32 v113, v113, v227
	v_mul_f32_e32 v113, v113, v199
	v_fma_f32 v113, v113, v231, v149
	v_mul_f32_e32 v114, v114, v227
	v_mul_f32_e32 v114, v114, v200
	v_fma_f32 v114, v114, v231, v150
	v_mul_f32_e32 v115, v115, v227
	v_mul_f32_e32 v115, v115, v201
	v_fma_f32 v115, v115, v231, v151
	v_mul_f32_e32 v92, v92, v228
	v_mul_f32_e32 v92, v92, v198
	v_fma_f32 v92, v92, v232, v152
	v_mul_f32_e32 v93, v93, v228
	v_mul_f32_e32 v93, v93, v199
	v_fma_f32 v93, v93, v232, v153
	v_mul_f32_e32 v94, v94, v228
	v_mul_f32_e32 v94, v94, v200
	v_fma_f32 v94, v94, v232, v154
	v_mul_f32_e32 v95, v95, v228
	v_mul_f32_e32 v95, v95, v201
	v_fma_f32 v95, v95, v232, v155
	v_mul_f32_e32 v88, v88, v229
	v_mul_f32_e32 v88, v88, v198
	v_fma_f32 v88, v88, v233, v156
	v_mul_f32_e32 v89, v89, v229
	v_mul_f32_e32 v89, v89, v199
	v_fma_f32 v89, v89, v233, v157
	v_mul_f32_e32 v90, v90, v229
	v_mul_f32_e32 v90, v90, v200
	v_fma_f32 v90, v90, v233, v158
	v_mul_f32_e32 v91, v91, v229
	v_mul_f32_e32 v91, v91, v201
	v_fma_f32 v91, v91, v233, v159
	global_store_dword v176, v116, s[36:37]
	global_store_dword v177, v117, s[36:37]
	global_store_dword v178, v118, s[36:37]
	global_store_dword v179, v119, s[36:37]
	global_store_dword v176, v112, s[36:37] offset:64
	global_store_dword v177, v113, s[36:37] offset:64
	global_store_dword v178, v114, s[36:37] offset:64
	global_store_dword v179, v115, s[36:37] offset:64
	global_store_dword v176, v92, s[36:37] offset:512
	global_store_dword v177, v93, s[36:37] offset:512
	global_store_dword v178, v94, s[36:37] offset:512
	global_store_dword v179, v95, s[36:37] offset:512
	global_store_dword v176, v88, s[36:37] offset:576
	global_store_dword v177, v89, s[36:37] offset:576
	global_store_dword v178, v90, s[36:37] offset:576
	global_store_dword v179, v91, s[36:37] offset:576
	v_add_u32_e32 v176, 0x60000, v168
	v_add_u32_e32 v177, 0x60000, v169
	v_add_u32_e32 v178, 0x60000, v170
	v_add_u32_e32 v179, 0x60000, v171
	global_load_dword v144, v176, s[0:1]
	global_load_dword v145, v177, s[0:1]
	global_load_dword v146, v178, s[0:1]
	global_load_dword v147, v179, s[0:1]
	global_load_dword v148, v176, s[0:1] offset:64
	global_load_dword v149, v177, s[0:1] offset:64
	global_load_dword v150, v178, s[0:1] offset:64
	global_load_dword v151, v179, s[0:1] offset:64
	global_load_dword v152, v176, s[0:1] offset:512
	global_load_dword v153, v177, s[0:1] offset:512
	global_load_dword v154, v178, s[0:1] offset:512
	global_load_dword v155, v179, s[0:1] offset:512
	global_load_dword v156, v176, s[0:1] offset:576
	global_load_dword v157, v177, s[0:1] offset:576
	global_load_dword v158, v178, s[0:1] offset:576
	global_load_dword v159, v179, s[0:1] offset:576
	s_waitcnt vmcnt(32)
	v_mul_f32_e32 v108, v108, v226
	v_mul_f32_e32 v108, v108, v202
	v_fma_f32 v108, v108, v230, v128
	v_mul_f32_e32 v109, v109, v226
	v_mul_f32_e32 v109, v109, v203
	v_fma_f32 v109, v109, v230, v129
	v_mul_f32_e32 v110, v110, v226
	v_mul_f32_e32 v110, v110, v204
	v_fma_f32 v110, v110, v230, v130
	v_mul_f32_e32 v111, v111, v226
	v_mul_f32_e32 v111, v111, v205
	v_fma_f32 v111, v111, v230, v131
	v_mul_f32_e32 v104, v104, v227
	v_mul_f32_e32 v104, v104, v202
	v_fma_f32 v104, v104, v231, v132
	v_mul_f32_e32 v105, v105, v227
	v_mul_f32_e32 v105, v105, v203
	v_fma_f32 v105, v105, v231, v133
	v_mul_f32_e32 v106, v106, v227
	v_mul_f32_e32 v106, v106, v204
	v_fma_f32 v106, v106, v231, v134
	v_mul_f32_e32 v107, v107, v227
	v_mul_f32_e32 v107, v107, v205
	v_fma_f32 v107, v107, v231, v135
	v_mul_f32_e32 v80, v80, v228
	v_mul_f32_e32 v80, v80, v202
	v_fma_f32 v80, v80, v232, v136
	v_mul_f32_e32 v81, v81, v228
	v_mul_f32_e32 v81, v81, v203
	v_fma_f32 v81, v81, v232, v137
	v_mul_f32_e32 v82, v82, v228
	v_mul_f32_e32 v82, v82, v204
	v_fma_f32 v82, v82, v232, v138
	v_mul_f32_e32 v83, v83, v228
	v_mul_f32_e32 v83, v83, v205
	v_fma_f32 v83, v83, v232, v139
	v_mul_f32_e32 v72, v72, v229
	v_mul_f32_e32 v72, v72, v202
	v_fma_f32 v72, v72, v233, v140
	v_mul_f32_e32 v73, v73, v229
	v_mul_f32_e32 v73, v73, v203
	v_fma_f32 v73, v73, v233, v141
	v_mul_f32_e32 v74, v74, v229
	v_mul_f32_e32 v74, v74, v204
	v_fma_f32 v74, v74, v233, v142
	v_mul_f32_e32 v75, v75, v229
	v_mul_f32_e32 v75, v75, v205
	v_fma_f32 v75, v75, v233, v143
	global_store_dword v172, v108, s[36:37]
	global_store_dword v173, v109, s[36:37]
	global_store_dword v174, v110, s[36:37]
	global_store_dword v175, v111, s[36:37]
	global_store_dword v172, v104, s[36:37] offset:64
	global_store_dword v173, v105, s[36:37] offset:64
	global_store_dword v174, v106, s[36:37] offset:64
	global_store_dword v175, v107, s[36:37] offset:64
	global_store_dword v172, v80, s[36:37] offset:512
	global_store_dword v173, v81, s[36:37] offset:512
	global_store_dword v174, v82, s[36:37] offset:512
	global_store_dword v175, v83, s[36:37] offset:512
	global_store_dword v172, v72, s[36:37] offset:576
	global_store_dword v173, v73, s[36:37] offset:576
	global_store_dword v174, v74, s[36:37] offset:576
	global_store_dword v175, v75, s[36:37] offset:576
	v_add_u32_e32 v172, 0x100000, v168
	v_add_u32_e32 v173, 0x100000, v169
	v_add_u32_e32 v174, 0x100000, v170
	v_add_u32_e32 v175, 0x100000, v171
	global_load_dword v128, v172, s[0:1]
	global_load_dword v129, v173, s[0:1]
	global_load_dword v130, v174, s[0:1]
	global_load_dword v131, v175, s[0:1]
	global_load_dword v132, v172, s[0:1] offset:64
	global_load_dword v133, v173, s[0:1] offset:64
	global_load_dword v134, v174, s[0:1] offset:64
	global_load_dword v135, v175, s[0:1] offset:64
	global_load_dword v136, v172, s[0:1] offset:512
	global_load_dword v137, v173, s[0:1] offset:512
	global_load_dword v138, v174, s[0:1] offset:512
	global_load_dword v139, v175, s[0:1] offset:512
	global_load_dword v140, v172, s[0:1] offset:576
	global_load_dword v141, v173, s[0:1] offset:576
	global_load_dword v142, v174, s[0:1] offset:576
	global_load_dword v143, v175, s[0:1] offset:576
	s_waitcnt vmcnt(32)
	v_mul_f32_e32 v84, v84, v226
	v_mul_f32_e32 v84, v84, v206
	v_fma_f32 v84, v84, v230, v144
	v_mul_f32_e32 v85, v85, v226
	v_mul_f32_e32 v85, v85, v207
	v_fma_f32 v85, v85, v230, v145
	v_mul_f32_e32 v86, v86, v226
	v_mul_f32_e32 v86, v86, v208
	v_fma_f32 v86, v86, v230, v146
	v_mul_f32_e32 v87, v87, v226
	v_mul_f32_e32 v87, v87, v209
	v_fma_f32 v87, v87, v230, v147
	v_mul_f32_e32 v76, v76, v227
	v_mul_f32_e32 v76, v76, v206
	v_fma_f32 v76, v76, v231, v148
	v_mul_f32_e32 v77, v77, v227
	v_mul_f32_e32 v77, v77, v207
	v_fma_f32 v77, v77, v231, v149
	v_mul_f32_e32 v78, v78, v227
	v_mul_f32_e32 v78, v78, v208
	v_fma_f32 v78, v78, v231, v150
	v_mul_f32_e32 v79, v79, v227
	v_mul_f32_e32 v79, v79, v209
	v_fma_f32 v79, v79, v231, v151
	v_mul_f32_e32 v68, v68, v228
	v_mul_f32_e32 v68, v68, v206
	v_fma_f32 v68, v68, v232, v152
	v_mul_f32_e32 v69, v69, v228
	v_mul_f32_e32 v69, v69, v207
	v_fma_f32 v69, v69, v232, v153
	v_mul_f32_e32 v70, v70, v228
	v_mul_f32_e32 v70, v70, v208
	v_fma_f32 v70, v70, v232, v154
	v_mul_f32_e32 v71, v71, v228
	v_mul_f32_e32 v71, v71, v209
	v_fma_f32 v71, v71, v232, v155
	v_mul_f32_e32 v64, v64, v229
	v_mul_f32_e32 v64, v64, v206
	v_fma_f32 v64, v64, v233, v156
	v_mul_f32_e32 v65, v65, v229
	v_mul_f32_e32 v65, v65, v207
	v_fma_f32 v65, v65, v233, v157
	v_mul_f32_e32 v66, v66, v229
	v_mul_f32_e32 v66, v66, v208
	v_fma_f32 v66, v66, v233, v158
	v_mul_f32_e32 v67, v67, v229
	v_mul_f32_e32 v67, v67, v209
	v_fma_f32 v67, v67, v233, v159
	global_store_dword v176, v84, s[36:37]
	global_store_dword v177, v85, s[36:37]
	global_store_dword v178, v86, s[36:37]
	global_store_dword v179, v87, s[36:37]
	global_store_dword v176, v76, s[36:37] offset:64
	global_store_dword v177, v77, s[36:37] offset:64
	global_store_dword v178, v78, s[36:37] offset:64
	global_store_dword v179, v79, s[36:37] offset:64
	global_store_dword v176, v68, s[36:37] offset:512
	global_store_dword v177, v69, s[36:37] offset:512
	global_store_dword v178, v70, s[36:37] offset:512
	global_store_dword v179, v71, s[36:37] offset:512
	global_store_dword v176, v64, s[36:37] offset:576
	global_store_dword v177, v65, s[36:37] offset:576
	global_store_dword v178, v66, s[36:37] offset:576
	global_store_dword v179, v67, s[36:37] offset:576
	v_add_u32_e32 v176, 0x120000, v168
	v_add_u32_e32 v177, 0x120000, v169
	v_add_u32_e32 v178, 0x120000, v170
	v_add_u32_e32 v179, 0x120000, v171
	global_load_dword v144, v176, s[0:1]
	global_load_dword v145, v177, s[0:1]
	global_load_dword v146, v178, s[0:1]
	global_load_dword v147, v179, s[0:1]
	global_load_dword v148, v176, s[0:1] offset:64
	global_load_dword v149, v177, s[0:1] offset:64
	global_load_dword v150, v178, s[0:1] offset:64
	global_load_dword v151, v179, s[0:1] offset:64
	global_load_dword v152, v176, s[0:1] offset:512
	global_load_dword v153, v177, s[0:1] offset:512
	global_load_dword v154, v178, s[0:1] offset:512
	global_load_dword v155, v179, s[0:1] offset:512
	global_load_dword v156, v176, s[0:1] offset:576
	global_load_dword v157, v177, s[0:1] offset:576
	global_load_dword v158, v178, s[0:1] offset:576
	global_load_dword v159, v179, s[0:1] offset:576
	s_waitcnt vmcnt(32)
	v_mul_f32_e32 v60, v60, v226
	v_mul_f32_e32 v60, v60, v210
	v_fma_f32 v60, v60, v230, v128
	v_mul_f32_e32 v61, v61, v226
	v_mul_f32_e32 v61, v61, v211
	v_fma_f32 v61, v61, v230, v129
	v_mul_f32_e32 v62, v62, v226
	v_mul_f32_e32 v62, v62, v212
	v_fma_f32 v62, v62, v230, v130
	v_mul_f32_e32 v63, v63, v226
	v_mul_f32_e32 v63, v63, v213
	v_fma_f32 v63, v63, v230, v131
	v_mul_f32_e32 v56, v56, v227
	v_mul_f32_e32 v56, v56, v210
	v_fma_f32 v56, v56, v231, v132
	v_mul_f32_e32 v57, v57, v227
	v_mul_f32_e32 v57, v57, v211
	v_fma_f32 v57, v57, v231, v133
	v_mul_f32_e32 v58, v58, v227
	v_mul_f32_e32 v58, v58, v212
	v_fma_f32 v58, v58, v231, v134
	v_mul_f32_e32 v59, v59, v227
	v_mul_f32_e32 v59, v59, v213
	v_fma_f32 v59, v59, v231, v135
	v_mul_f32_e32 v32, v32, v228
	v_mul_f32_e32 v32, v32, v210
	v_fma_f32 v32, v32, v232, v136
	v_mul_f32_e32 v33, v33, v228
	v_mul_f32_e32 v33, v33, v211
	v_fma_f32 v33, v33, v232, v137
	v_mul_f32_e32 v34, v34, v228
	v_mul_f32_e32 v34, v34, v212
	v_fma_f32 v34, v34, v232, v138
	v_mul_f32_e32 v35, v35, v228
	v_mul_f32_e32 v35, v35, v213
	v_fma_f32 v35, v35, v232, v139
	v_mul_f32_e32 v24, v24, v229
	v_mul_f32_e32 v24, v24, v210
	v_fma_f32 v24, v24, v233, v140
	v_mul_f32_e32 v25, v25, v229
	v_mul_f32_e32 v25, v25, v211
	v_fma_f32 v25, v25, v233, v141
	v_mul_f32_e32 v26, v26, v229
	v_mul_f32_e32 v26, v26, v212
	v_fma_f32 v26, v26, v233, v142
	v_mul_f32_e32 v27, v27, v229
	v_mul_f32_e32 v27, v27, v213
	v_fma_f32 v27, v27, v233, v143
	global_store_dword v172, v60, s[36:37]
	global_store_dword v173, v61, s[36:37]
	global_store_dword v174, v62, s[36:37]
	global_store_dword v175, v63, s[36:37]
	global_store_dword v172, v56, s[36:37] offset:64
	global_store_dword v173, v57, s[36:37] offset:64
	global_store_dword v174, v58, s[36:37] offset:64
	global_store_dword v175, v59, s[36:37] offset:64
	global_store_dword v172, v32, s[36:37] offset:512
	global_store_dword v173, v33, s[36:37] offset:512
	global_store_dword v174, v34, s[36:37] offset:512
	global_store_dword v175, v35, s[36:37] offset:512
	global_store_dword v172, v24, s[36:37] offset:576
	global_store_dword v173, v25, s[36:37] offset:576
	global_store_dword v174, v26, s[36:37] offset:576
	global_store_dword v175, v27, s[36:37] offset:576
	v_add_u32_e32 v172, 0x140000, v168
	v_add_u32_e32 v173, 0x140000, v169
	v_add_u32_e32 v174, 0x140000, v170
	v_add_u32_e32 v175, 0x140000, v171
	global_load_dword v128, v172, s[0:1]
	global_load_dword v129, v173, s[0:1]
	global_load_dword v130, v174, s[0:1]
	global_load_dword v131, v175, s[0:1]
	global_load_dword v132, v172, s[0:1] offset:64
	global_load_dword v133, v173, s[0:1] offset:64
	global_load_dword v134, v174, s[0:1] offset:64
	global_load_dword v135, v175, s[0:1] offset:64
	global_load_dword v136, v172, s[0:1] offset:512
	global_load_dword v137, v173, s[0:1] offset:512
	global_load_dword v138, v174, s[0:1] offset:512
	global_load_dword v139, v175, s[0:1] offset:512
	global_load_dword v140, v172, s[0:1] offset:576
	global_load_dword v141, v173, s[0:1] offset:576
	global_load_dword v142, v174, s[0:1] offset:576
	global_load_dword v143, v175, s[0:1] offset:576
	s_waitcnt vmcnt(32)
	v_mul_f32_e32 v52, v52, v226
	v_mul_f32_e32 v52, v52, v214
	v_fma_f32 v52, v52, v230, v144
	v_mul_f32_e32 v53, v53, v226
	v_mul_f32_e32 v53, v53, v215
	v_fma_f32 v53, v53, v230, v145
	v_mul_f32_e32 v54, v54, v226
	v_mul_f32_e32 v54, v54, v216
	v_fma_f32 v54, v54, v230, v146
	v_mul_f32_e32 v55, v55, v226
	v_mul_f32_e32 v55, v55, v217
	v_fma_f32 v55, v55, v230, v147
	v_mul_f32_e32 v48, v48, v227
	v_mul_f32_e32 v48, v48, v214
	v_fma_f32 v48, v48, v231, v148
	v_mul_f32_e32 v49, v49, v227
	v_mul_f32_e32 v49, v49, v215
	v_fma_f32 v49, v49, v231, v149
	v_mul_f32_e32 v50, v50, v227
	v_mul_f32_e32 v50, v50, v216
	v_fma_f32 v50, v50, v231, v150
	v_mul_f32_e32 v51, v51, v227
	v_mul_f32_e32 v51, v51, v217
	v_fma_f32 v51, v51, v231, v151
	v_mul_f32_e32 v20, v20, v228
	v_mul_f32_e32 v20, v20, v214
	v_fma_f32 v20, v20, v232, v152
	v_mul_f32_e32 v21, v21, v228
	v_mul_f32_e32 v21, v21, v215
	v_fma_f32 v21, v21, v232, v153
	v_mul_f32_e32 v22, v22, v228
	v_mul_f32_e32 v22, v22, v216
	v_fma_f32 v22, v22, v232, v154
	v_mul_f32_e32 v23, v23, v228
	v_mul_f32_e32 v23, v23, v217
	v_fma_f32 v23, v23, v232, v155
	v_mul_f32_e32 v16, v16, v229
	v_mul_f32_e32 v16, v16, v214
	v_fma_f32 v16, v16, v233, v156
	v_mul_f32_e32 v17, v17, v229
	v_mul_f32_e32 v17, v17, v215
	v_fma_f32 v17, v17, v233, v157
	v_mul_f32_e32 v18, v18, v229
	v_mul_f32_e32 v18, v18, v216
	v_fma_f32 v18, v18, v233, v158
	v_mul_f32_e32 v19, v19, v229
	v_mul_f32_e32 v19, v19, v217
	v_fma_f32 v19, v19, v233, v159
	global_store_dword v176, v52, s[36:37]
	global_store_dword v177, v53, s[36:37]
	global_store_dword v178, v54, s[36:37]
	global_store_dword v179, v55, s[36:37]
	global_store_dword v176, v48, s[36:37] offset:64
	global_store_dword v177, v49, s[36:37] offset:64
	global_store_dword v178, v50, s[36:37] offset:64
	global_store_dword v179, v51, s[36:37] offset:64
	global_store_dword v176, v20, s[36:37] offset:512
	global_store_dword v177, v21, s[36:37] offset:512
	global_store_dword v178, v22, s[36:37] offset:512
	global_store_dword v179, v23, s[36:37] offset:512
	global_store_dword v176, v16, s[36:37] offset:576
	global_store_dword v177, v17, s[36:37] offset:576
	global_store_dword v178, v18, s[36:37] offset:576
	global_store_dword v179, v19, s[36:37] offset:576
	v_add_u32_e32 v176, 0x160000, v168
	v_add_u32_e32 v177, 0x160000, v169
	v_add_u32_e32 v178, 0x160000, v170
	v_add_u32_e32 v179, 0x160000, v171
	global_load_dword v144, v176, s[0:1]
	global_load_dword v145, v177, s[0:1]
	global_load_dword v146, v178, s[0:1]
	global_load_dword v147, v179, s[0:1]
	global_load_dword v148, v176, s[0:1] offset:64
	global_load_dword v149, v177, s[0:1] offset:64
	global_load_dword v150, v178, s[0:1] offset:64
	global_load_dword v151, v179, s[0:1] offset:64
	global_load_dword v152, v176, s[0:1] offset:512
	global_load_dword v153, v177, s[0:1] offset:512
	global_load_dword v154, v178, s[0:1] offset:512
	global_load_dword v155, v179, s[0:1] offset:512
	global_load_dword v156, v176, s[0:1] offset:576
	global_load_dword v157, v177, s[0:1] offset:576
	global_load_dword v158, v178, s[0:1] offset:576
	global_load_dword v159, v179, s[0:1] offset:576
	s_waitcnt vmcnt(32)
	v_mul_f32_e32 v44, v44, v226
	v_mul_f32_e32 v44, v44, v218
	v_fma_f32 v44, v44, v230, v128
	v_mul_f32_e32 v45, v45, v226
	v_mul_f32_e32 v45, v45, v219
	v_fma_f32 v45, v45, v230, v129
	v_mul_f32_e32 v46, v46, v226
	v_mul_f32_e32 v46, v46, v220
	v_fma_f32 v46, v46, v230, v130
	v_mul_f32_e32 v47, v47, v226
	v_mul_f32_e32 v47, v47, v221
	v_fma_f32 v47, v47, v230, v131
	v_mul_f32_e32 v40, v40, v227
	v_mul_f32_e32 v40, v40, v218
	v_fma_f32 v40, v40, v231, v132
	v_mul_f32_e32 v41, v41, v227
	v_mul_f32_e32 v41, v41, v219
	v_fma_f32 v41, v41, v231, v133
	v_mul_f32_e32 v42, v42, v227
	v_mul_f32_e32 v42, v42, v220
	v_fma_f32 v42, v42, v231, v134
	v_mul_f32_e32 v43, v43, v227
	v_mul_f32_e32 v43, v43, v221
	v_fma_f32 v43, v43, v231, v135
	v_mul_f32_e32 v12, v12, v228
	v_mul_f32_e32 v12, v12, v218
	v_fma_f32 v12, v12, v232, v136
	v_mul_f32_e32 v13, v13, v228
	v_mul_f32_e32 v13, v13, v219
	v_fma_f32 v13, v13, v232, v137
	v_mul_f32_e32 v14, v14, v228
	v_mul_f32_e32 v14, v14, v220
	v_fma_f32 v14, v14, v232, v138
	v_mul_f32_e32 v15, v15, v228
	v_mul_f32_e32 v15, v15, v221
	v_fma_f32 v15, v15, v232, v139
	v_mul_f32_e32 v8, v8, v229
	v_mul_f32_e32 v8, v8, v218
	v_fma_f32 v8, v8, v233, v140
	v_mul_f32_e32 v9, v9, v229
	v_mul_f32_e32 v9, v9, v219
	v_fma_f32 v9, v9, v233, v141
	v_mul_f32_e32 v10, v10, v229
	v_mul_f32_e32 v10, v10, v220
	v_fma_f32 v10, v10, v233, v142
	v_mul_f32_e32 v11, v11, v229
	v_mul_f32_e32 v11, v11, v221
	v_fma_f32 v11, v11, v233, v143
	global_store_dword v172, v44, s[36:37]
	global_store_dword v173, v45, s[36:37]
	global_store_dword v174, v46, s[36:37]
	global_store_dword v175, v47, s[36:37]
	global_store_dword v172, v40, s[36:37] offset:64
	global_store_dword v173, v41, s[36:37] offset:64
	global_store_dword v174, v42, s[36:37] offset:64
	global_store_dword v175, v43, s[36:37] offset:64
	global_store_dword v172, v12, s[36:37] offset:512
	global_store_dword v173, v13, s[36:37] offset:512
	global_store_dword v174, v14, s[36:37] offset:512
	global_store_dword v175, v15, s[36:37] offset:512
	global_store_dword v172, v8, s[36:37] offset:576
	global_store_dword v173, v9, s[36:37] offset:576
	global_store_dword v174, v10, s[36:37] offset:576
	global_store_dword v175, v11, s[36:37] offset:576
	s_waitcnt vmcnt(16)
	v_mul_f32_e32 v36, v36, v226
	v_mul_f32_e32 v36, v36, v222
	v_fma_f32 v36, v36, v230, v144
	v_mul_f32_e32 v37, v37, v226
	v_mul_f32_e32 v37, v37, v223
	v_fma_f32 v37, v37, v230, v145
	v_mul_f32_e32 v38, v38, v226
	v_mul_f32_e32 v38, v38, v224
	v_fma_f32 v38, v38, v230, v146
	v_mul_f32_e32 v39, v39, v226
	v_mul_f32_e32 v39, v39, v225
	v_fma_f32 v39, v39, v230, v147
	v_mul_f32_e32 v28, v28, v227
	v_mul_f32_e32 v28, v28, v222
	v_fma_f32 v28, v28, v231, v148
	v_mul_f32_e32 v29, v29, v227
	v_mul_f32_e32 v29, v29, v223
	v_fma_f32 v29, v29, v231, v149
	v_mul_f32_e32 v30, v30, v227
	v_mul_f32_e32 v30, v30, v224
	v_fma_f32 v30, v30, v231, v150
	v_mul_f32_e32 v31, v31, v227
	v_mul_f32_e32 v31, v31, v225
	v_fma_f32 v31, v31, v231, v151
	v_mul_f32_e32 v4, v4, v228
	v_mul_f32_e32 v4, v4, v222
	v_fma_f32 v4, v4, v232, v152
	v_mul_f32_e32 v5, v5, v228
	v_mul_f32_e32 v5, v5, v223
	v_fma_f32 v5, v5, v232, v153
	v_mul_f32_e32 v6, v6, v228
	v_mul_f32_e32 v6, v6, v224
	v_fma_f32 v6, v6, v232, v154
	v_mul_f32_e32 v7, v7, v228
	v_mul_f32_e32 v7, v7, v225
	v_fma_f32 v7, v7, v232, v155
	v_mul_f32_e32 v0, v0, v229
	v_mul_f32_e32 v0, v0, v222
	v_fma_f32 v0, v0, v233, v156
	v_mul_f32_e32 v1, v1, v229
	v_mul_f32_e32 v1, v1, v223
	v_fma_f32 v1, v1, v233, v157
	v_mul_f32_e32 v2, v2, v229
	v_mul_f32_e32 v2, v2, v224
	v_fma_f32 v2, v2, v233, v158
	v_mul_f32_e32 v3, v3, v229
	v_mul_f32_e32 v3, v3, v225
	v_fma_f32 v3, v3, v233, v159
	global_store_dword v176, v36, s[36:37]
	global_store_dword v177, v37, s[36:37]
	global_store_dword v178, v38, s[36:37]
	global_store_dword v179, v39, s[36:37]
	global_store_dword v176, v28, s[36:37] offset:64
	global_store_dword v177, v29, s[36:37] offset:64
	global_store_dword v178, v30, s[36:37] offset:64
	global_store_dword v179, v31, s[36:37] offset:64
	global_store_dword v176, v4, s[36:37] offset:512
	global_store_dword v177, v5, s[36:37] offset:512
	global_store_dword v178, v6, s[36:37] offset:512
	global_store_dword v179, v7, s[36:37] offset:512
	global_store_dword v176, v0, s[36:37] offset:576
	global_store_dword v177, v1, s[36:37] offset:576
	global_store_dword v178, v2, s[36:37] offset:576
	global_store_dword v179, v3, s[36:37] offset:576
	v_readlane_b32 s57, v255, 0
	s_cmp_eq_u32 s57, 0
	s_cbranch_scc0 .Lgo_p2_end
	s_load_dwordx2 s[0:1], s[88:89], 0x30
	s_load_dwordx2 s[2:3], s[88:89], 0xf0
	s_load_dwordx2 s[34:35], s[88:89], 0x110
	v_mul_f32_e32 v194, v124, v124
	v_fmac_f32_e32 v194, v120, v120
	v_fmac_f32_e32 v194, v100, v100
	v_fmac_f32_e32 v194, v96, v96
	v_mul_f32_e32 v195, v125, v125
	v_fmac_f32_e32 v195, v121, v121
	v_fmac_f32_e32 v195, v101, v101
	v_fmac_f32_e32 v195, v97, v97
	v_mul_f32_e32 v196, v126, v126
	v_fmac_f32_e32 v196, v122, v122
	v_fmac_f32_e32 v196, v102, v102
	v_fmac_f32_e32 v196, v98, v98
	v_mul_f32_e32 v197, v127, v127
	v_fmac_f32_e32 v197, v123, v123
	v_fmac_f32_e32 v197, v103, v103
	v_fmac_f32_e32 v197, v99, v99
	v_mul_f32_e32 v198, v116, v116
	v_fmac_f32_e32 v198, v112, v112
	v_fmac_f32_e32 v198, v92, v92
	v_fmac_f32_e32 v198, v88, v88
	v_mul_f32_e32 v199, v117, v117
	v_fmac_f32_e32 v199, v113, v113
	v_fmac_f32_e32 v199, v93, v93
	v_fmac_f32_e32 v199, v89, v89
	v_mul_f32_e32 v200, v118, v118
	v_fmac_f32_e32 v200, v114, v114
	v_fmac_f32_e32 v200, v94, v94
	v_fmac_f32_e32 v200, v90, v90
	v_mul_f32_e32 v201, v119, v119
	v_fmac_f32_e32 v201, v115, v115
	v_fmac_f32_e32 v201, v95, v95
	v_fmac_f32_e32 v201, v91, v91
	v_mul_f32_e32 v202, v108, v108
	v_fmac_f32_e32 v202, v104, v104
	v_fmac_f32_e32 v202, v80, v80
	v_fmac_f32_e32 v202, v72, v72
	v_mul_f32_e32 v203, v109, v109
	v_fmac_f32_e32 v203, v105, v105
	v_fmac_f32_e32 v203, v81, v81
	v_fmac_f32_e32 v203, v73, v73
	v_mul_f32_e32 v204, v110, v110
	v_fmac_f32_e32 v204, v106, v106
	v_fmac_f32_e32 v204, v82, v82
	v_fmac_f32_e32 v204, v74, v74
	v_mul_f32_e32 v205, v111, v111
	v_fmac_f32_e32 v205, v107, v107
	v_fmac_f32_e32 v205, v83, v83
	v_fmac_f32_e32 v205, v75, v75
	v_mul_f32_e32 v206, v84, v84
	v_fmac_f32_e32 v206, v76, v76
	v_fmac_f32_e32 v206, v68, v68
	v_fmac_f32_e32 v206, v64, v64
	v_mul_f32_e32 v207, v85, v85
	v_fmac_f32_e32 v207, v77, v77
	v_fmac_f32_e32 v207, v69, v69
	v_fmac_f32_e32 v207, v65, v65
	v_mul_f32_e32 v208, v86, v86
	v_fmac_f32_e32 v208, v78, v78
	v_fmac_f32_e32 v208, v70, v70
	v_fmac_f32_e32 v208, v66, v66
	v_mul_f32_e32 v209, v87, v87
	v_fmac_f32_e32 v209, v79, v79
	v_fmac_f32_e32 v209, v71, v71
	v_fmac_f32_e32 v209, v67, v67
	v_mul_f32_e32 v210, v60, v60
	v_fmac_f32_e32 v210, v56, v56
	v_fmac_f32_e32 v210, v32, v32
	v_fmac_f32_e32 v210, v24, v24
	v_mul_f32_e32 v211, v61, v61
	v_fmac_f32_e32 v211, v57, v57
	v_fmac_f32_e32 v211, v33, v33
	v_fmac_f32_e32 v211, v25, v25
	v_mul_f32_e32 v212, v62, v62
	v_fmac_f32_e32 v212, v58, v58
	v_fmac_f32_e32 v212, v34, v34
	v_fmac_f32_e32 v212, v26, v26
	v_mul_f32_e32 v213, v63, v63
	v_fmac_f32_e32 v213, v59, v59
	v_fmac_f32_e32 v213, v35, v35
	v_fmac_f32_e32 v213, v27, v27
	v_mul_f32_e32 v214, v52, v52
	v_fmac_f32_e32 v214, v48, v48
	v_fmac_f32_e32 v214, v20, v20
	v_fmac_f32_e32 v214, v16, v16
	v_mul_f32_e32 v215, v53, v53
	v_fmac_f32_e32 v215, v49, v49
	v_fmac_f32_e32 v215, v21, v21
	v_fmac_f32_e32 v215, v17, v17
	v_mul_f32_e32 v216, v54, v54
	v_fmac_f32_e32 v216, v50, v50
	v_fmac_f32_e32 v216, v22, v22
	v_fmac_f32_e32 v216, v18, v18
	v_mul_f32_e32 v217, v55, v55
	v_fmac_f32_e32 v217, v51, v51
	v_fmac_f32_e32 v217, v23, v23
	v_fmac_f32_e32 v217, v19, v19
	v_mul_f32_e32 v218, v44, v44
	v_fmac_f32_e32 v218, v40, v40
	v_fmac_f32_e32 v218, v12, v12
	v_fmac_f32_e32 v218, v8, v8
	v_mul_f32_e32 v219, v45, v45
	v_fmac_f32_e32 v219, v41, v41
	v_fmac_f32_e32 v219, v13, v13
	v_fmac_f32_e32 v219, v9, v9
	v_mul_f32_e32 v220, v46, v46
	v_fmac_f32_e32 v220, v42, v42
	v_fmac_f32_e32 v220, v14, v14
	v_fmac_f32_e32 v220, v10, v10
	v_mul_f32_e32 v221, v47, v47
	v_fmac_f32_e32 v221, v43, v43
	v_fmac_f32_e32 v221, v15, v15
	v_fmac_f32_e32 v221, v11, v11
	v_mul_f32_e32 v222, v36, v36
	v_fmac_f32_e32 v222, v28, v28
	v_fmac_f32_e32 v222, v4, v4
	v_fmac_f32_e32 v222, v0, v0
	v_mul_f32_e32 v223, v37, v37
	v_fmac_f32_e32 v223, v29, v29
	v_fmac_f32_e32 v223, v5, v5
	v_fmac_f32_e32 v223, v1, v1
	v_mul_f32_e32 v224, v38, v38
	v_fmac_f32_e32 v224, v30, v30
	v_fmac_f32_e32 v224, v6, v6
	v_fmac_f32_e32 v224, v2, v2
	v_mul_f32_e32 v225, v39, v39
	v_fmac_f32_e32 v225, v31, v31
	v_fmac_f32_e32 v225, v7, v7
	v_fmac_f32_e32 v225, v3, v3
	s_nop 1
	v_add_f32_dpp v194, v194, v194 row_ror:8 row_mask:0xf bank_mask:0xf
	v_add_f32_dpp v195, v195, v195 row_ror:8 row_mask:0xf bank_mask:0xf
	v_add_f32_dpp v196, v196, v196 row_ror:8 row_mask:0xf bank_mask:0xf
	v_add_f32_dpp v197, v197, v197 row_ror:8 row_mask:0xf bank_mask:0xf
	v_add_f32_dpp v198, v198, v198 row_ror:8 row_mask:0xf bank_mask:0xf
	v_add_f32_dpp v199, v199, v199 row_ror:8 row_mask:0xf bank_mask:0xf
	v_add_f32_dpp v200, v200, v200 row_ror:8 row_mask:0xf bank_mask:0xf
	v_add_f32_dpp v201, v201, v201 row_ror:8 row_mask:0xf bank_mask:0xf
	v_add_f32_dpp v202, v202, v202 row_ror:8 row_mask:0xf bank_mask:0xf
	v_add_f32_dpp v203, v203, v203 row_ror:8 row_mask:0xf bank_mask:0xf
	v_add_f32_dpp v204, v204, v204 row_ror:8 row_mask:0xf bank_mask:0xf
	v_add_f32_dpp v205, v205, v205 row_ror:8 row_mask:0xf bank_mask:0xf
	v_add_f32_dpp v206, v206, v206 row_ror:8 row_mask:0xf bank_mask:0xf
	v_add_f32_dpp v207, v207, v207 row_ror:8 row_mask:0xf bank_mask:0xf
	v_add_f32_dpp v208, v208, v208 row_ror:8 row_mask:0xf bank_mask:0xf
	v_add_f32_dpp v209, v209, v209 row_ror:8 row_mask:0xf bank_mask:0xf
	v_add_f32_dpp v210, v210, v210 row_ror:8 row_mask:0xf bank_mask:0xf
	v_add_f32_dpp v211, v211, v211 row_ror:8 row_mask:0xf bank_mask:0xf
	v_add_f32_dpp v212, v212, v212 row_ror:8 row_mask:0xf bank_mask:0xf
	v_add_f32_dpp v213, v213, v213 row_ror:8 row_mask:0xf bank_mask:0xf
	v_add_f32_dpp v214, v214, v214 row_ror:8 row_mask:0xf bank_mask:0xf
	v_add_f32_dpp v215, v215, v215 row_ror:8 row_mask:0xf bank_mask:0xf
	v_add_f32_dpp v216, v216, v216 row_ror:8 row_mask:0xf bank_mask:0xf
	v_add_f32_dpp v217, v217, v217 row_ror:8 row_mask:0xf bank_mask:0xf
	v_add_f32_dpp v218, v218, v218 row_ror:8 row_mask:0xf bank_mask:0xf
	v_add_f32_dpp v219, v219, v219 row_ror:8 row_mask:0xf bank_mask:0xf
	v_add_f32_dpp v220, v220, v220 row_ror:8 row_mask:0xf bank_mask:0xf
	v_add_f32_dpp v221, v221, v221 row_ror:8 row_mask:0xf bank_mask:0xf
	v_add_f32_dpp v222, v222, v222 row_ror:8 row_mask:0xf bank_mask:0xf
	v_add_f32_dpp v223, v223, v223 row_ror:8 row_mask:0xf bank_mask:0xf
	v_add_f32_dpp v224, v224, v224 row_ror:8 row_mask:0xf bank_mask:0xf
	v_add_f32_dpp v225, v225, v225 row_ror:8 row_mask:0xf bank_mask:0xf
	s_nop 1
	v_add_f32_dpp v194, v194, v194 row_ror:4 row_mask:0xf bank_mask:0xf
	v_add_f32_dpp v195, v195, v195 row_ror:4 row_mask:0xf bank_mask:0xf
	v_add_f32_dpp v196, v196, v196 row_ror:4 row_mask:0xf bank_mask:0xf
	v_add_f32_dpp v197, v197, v197 row_ror:4 row_mask:0xf bank_mask:0xf
	v_add_f32_dpp v198, v198, v198 row_ror:4 row_mask:0xf bank_mask:0xf
	v_add_f32_dpp v199, v199, v199 row_ror:4 row_mask:0xf bank_mask:0xf
	v_add_f32_dpp v200, v200, v200 row_ror:4 row_mask:0xf bank_mask:0xf
	v_add_f32_dpp v201, v201, v201 row_ror:4 row_mask:0xf bank_mask:0xf
	v_add_f32_dpp v202, v202, v202 row_ror:4 row_mask:0xf bank_mask:0xf
	v_add_f32_dpp v203, v203, v203 row_ror:4 row_mask:0xf bank_mask:0xf
	v_add_f32_dpp v204, v204, v204 row_ror:4 row_mask:0xf bank_mask:0xf
	v_add_f32_dpp v205, v205, v205 row_ror:4 row_mask:0xf bank_mask:0xf
	v_add_f32_dpp v206, v206, v206 row_ror:4 row_mask:0xf bank_mask:0xf
	v_add_f32_dpp v207, v207, v207 row_ror:4 row_mask:0xf bank_mask:0xf
	v_add_f32_dpp v208, v208, v208 row_ror:4 row_mask:0xf bank_mask:0xf
	v_add_f32_dpp v209, v209, v209 row_ror:4 row_mask:0xf bank_mask:0xf
	v_add_f32_dpp v210, v210, v210 row_ror:4 row_mask:0xf bank_mask:0xf
	v_add_f32_dpp v211, v211, v211 row_ror:4 row_mask:0xf bank_mask:0xf
	v_add_f32_dpp v212, v212, v212 row_ror:4 row_mask:0xf bank_mask:0xf
	v_add_f32_dpp v213, v213, v213 row_ror:4 row_mask:0xf bank_mask:0xf
	v_add_f32_dpp v214, v214, v214 row_ror:4 row_mask:0xf bank_mask:0xf
	v_add_f32_dpp v215, v215, v215 row_ror:4 row_mask:0xf bank_mask:0xf
	v_add_f32_dpp v216, v216, v216 row_ror:4 row_mask:0xf bank_mask:0xf
	v_add_f32_dpp v217, v217, v217 row_ror:4 row_mask:0xf bank_mask:0xf
	v_add_f32_dpp v218, v218, v218 row_ror:4 row_mask:0xf bank_mask:0xf
	v_add_f32_dpp v219, v219, v219 row_ror:4 row_mask:0xf bank_mask:0xf
	v_add_f32_dpp v220, v220, v220 row_ror:4 row_mask:0xf bank_mask:0xf
	v_add_f32_dpp v221, v221, v221 row_ror:4 row_mask:0xf bank_mask:0xf
	v_add_f32_dpp v222, v222, v222 row_ror:4 row_mask:0xf bank_mask:0xf
	v_add_f32_dpp v223, v223, v223 row_ror:4 row_mask:0xf bank_mask:0xf
	v_add_f32_dpp v224, v224, v224 row_ror:4 row_mask:0xf bank_mask:0xf
	v_add_f32_dpp v225, v225, v225 row_ror:4 row_mask:0xf bank_mask:0xf
	s_nop 1
	v_add_f32_dpp v194, v194, v194 row_ror:2 row_mask:0xf bank_mask:0xf
	v_add_f32_dpp v195, v195, v195 row_ror:2 row_mask:0xf bank_mask:0xf
	v_add_f32_dpp v196, v196, v196 row_ror:2 row_mask:0xf bank_mask:0xf
	v_add_f32_dpp v197, v197, v197 row_ror:2 row_mask:0xf bank_mask:0xf
	v_add_f32_dpp v198, v198, v198 row_ror:2 row_mask:0xf bank_mask:0xf
	v_add_f32_dpp v199, v199, v199 row_ror:2 row_mask:0xf bank_mask:0xf
	v_add_f32_dpp v200, v200, v200 row_ror:2 row_mask:0xf bank_mask:0xf
	v_add_f32_dpp v201, v201, v201 row_ror:2 row_mask:0xf bank_mask:0xf
	v_add_f32_dpp v202, v202, v202 row_ror:2 row_mask:0xf bank_mask:0xf
	v_add_f32_dpp v203, v203, v203 row_ror:2 row_mask:0xf bank_mask:0xf
	v_add_f32_dpp v204, v204, v204 row_ror:2 row_mask:0xf bank_mask:0xf
	v_add_f32_dpp v205, v205, v205 row_ror:2 row_mask:0xf bank_mask:0xf
	v_add_f32_dpp v206, v206, v206 row_ror:2 row_mask:0xf bank_mask:0xf
	v_add_f32_dpp v207, v207, v207 row_ror:2 row_mask:0xf bank_mask:0xf
	v_add_f32_dpp v208, v208, v208 row_ror:2 row_mask:0xf bank_mask:0xf
	v_add_f32_dpp v209, v209, v209 row_ror:2 row_mask:0xf bank_mask:0xf
	v_add_f32_dpp v210, v210, v210 row_ror:2 row_mask:0xf bank_mask:0xf
	v_add_f32_dpp v211, v211, v211 row_ror:2 row_mask:0xf bank_mask:0xf
	v_add_f32_dpp v212, v212, v212 row_ror:2 row_mask:0xf bank_mask:0xf
	v_add_f32_dpp v213, v213, v213 row_ror:2 row_mask:0xf bank_mask:0xf
	v_add_f32_dpp v214, v214, v214 row_ror:2 row_mask:0xf bank_mask:0xf
	v_add_f32_dpp v215, v215, v215 row_ror:2 row_mask:0xf bank_mask:0xf
	v_add_f32_dpp v216, v216, v216 row_ror:2 row_mask:0xf bank_mask:0xf
	v_add_f32_dpp v217, v217, v217 row_ror:2 row_mask:0xf bank_mask:0xf
	v_add_f32_dpp v218, v218, v218 row_ror:2 row_mask:0xf bank_mask:0xf
	v_add_f32_dpp v219, v219, v219 row_ror:2 row_mask:0xf bank_mask:0xf
	v_add_f32_dpp v220, v220, v220 row_ror:2 row_mask:0xf bank_mask:0xf
	v_add_f32_dpp v221, v221, v221 row_ror:2 row_mask:0xf bank_mask:0xf
	v_add_f32_dpp v222, v222, v222 row_ror:2 row_mask:0xf bank_mask:0xf
	v_add_f32_dpp v223, v223, v223 row_ror:2 row_mask:0xf bank_mask:0xf
	v_add_f32_dpp v224, v224, v224 row_ror:2 row_mask:0xf bank_mask:0xf
	v_add_f32_dpp v225, v225, v225 row_ror:2 row_mask:0xf bank_mask:0xf
	s_nop 1
	v_add_f32_dpp v194, v194, v194 row_ror:1 row_mask:0xf bank_mask:0xf
	v_add_f32_dpp v195, v195, v195 row_ror:1 row_mask:0xf bank_mask:0xf
	v_add_f32_dpp v196, v196, v196 row_ror:1 row_mask:0xf bank_mask:0xf
	v_add_f32_dpp v197, v197, v197 row_ror:1 row_mask:0xf bank_mask:0xf
	v_add_f32_dpp v198, v198, v198 row_ror:1 row_mask:0xf bank_mask:0xf
	v_add_f32_dpp v199, v199, v199 row_ror:1 row_mask:0xf bank_mask:0xf
	v_add_f32_dpp v200, v200, v200 row_ror:1 row_mask:0xf bank_mask:0xf
	v_add_f32_dpp v201, v201, v201 row_ror:1 row_mask:0xf bank_mask:0xf
	v_add_f32_dpp v202, v202, v202 row_ror:1 row_mask:0xf bank_mask:0xf
	v_add_f32_dpp v203, v203, v203 row_ror:1 row_mask:0xf bank_mask:0xf
	v_add_f32_dpp v204, v204, v204 row_ror:1 row_mask:0xf bank_mask:0xf
	v_add_f32_dpp v205, v205, v205 row_ror:1 row_mask:0xf bank_mask:0xf
	v_add_f32_dpp v206, v206, v206 row_ror:1 row_mask:0xf bank_mask:0xf
	v_add_f32_dpp v207, v207, v207 row_ror:1 row_mask:0xf bank_mask:0xf
	v_add_f32_dpp v208, v208, v208 row_ror:1 row_mask:0xf bank_mask:0xf
	v_add_f32_dpp v209, v209, v209 row_ror:1 row_mask:0xf bank_mask:0xf
	v_add_f32_dpp v210, v210, v210 row_ror:1 row_mask:0xf bank_mask:0xf
	v_add_f32_dpp v211, v211, v211 row_ror:1 row_mask:0xf bank_mask:0xf
	v_add_f32_dpp v212, v212, v212 row_ror:1 row_mask:0xf bank_mask:0xf
	v_add_f32_dpp v213, v213, v213 row_ror:1 row_mask:0xf bank_mask:0xf
	v_add_f32_dpp v214, v214, v214 row_ror:1 row_mask:0xf bank_mask:0xf
	v_add_f32_dpp v215, v215, v215 row_ror:1 row_mask:0xf bank_mask:0xf
	v_add_f32_dpp v216, v216, v216 row_ror:1 row_mask:0xf bank_mask:0xf
	v_add_f32_dpp v217, v217, v217 row_ror:1 row_mask:0xf bank_mask:0xf
	v_add_f32_dpp v218, v218, v218 row_ror:1 row_mask:0xf bank_mask:0xf
	v_add_f32_dpp v219, v219, v219 row_ror:1 row_mask:0xf bank_mask:0xf
	v_add_f32_dpp v220, v220, v220 row_ror:1 row_mask:0xf bank_mask:0xf
	v_add_f32_dpp v221, v221, v221 row_ror:1 row_mask:0xf bank_mask:0xf
	v_add_f32_dpp v222, v222, v222 row_ror:1 row_mask:0xf bank_mask:0xf
	v_add_f32_dpp v223, v223, v223 row_ror:1 row_mask:0xf bank_mask:0xf
	v_add_f32_dpp v224, v224, v224 row_ror:1 row_mask:0xf bank_mask:0xf
	v_add_f32_dpp v225, v225, v225 row_ror:1 row_mask:0xf bank_mask:0xf
	v_lshlrev_b32_e32 v236, 10, v162
	v_lshl_add_u32 v236, v163, 2, v236
	v_add_u32_e32 v236, 0x21000, v236
	v_cmp_eq_u32_e32 vcc, 0, v160
	s_mov_b64 exec, vcc
	ds_write_b128 v236, v[194:197]
	ds_write_b128 v236, v[198:201] offset:64
	ds_write_b128 v236, v[202:205] offset:128
	ds_write_b128 v236, v[206:209] offset:192
	ds_write_b128 v236, v[210:213] offset:512
	ds_write_b128 v236, v[214:217] offset:576
	ds_write_b128 v236, v[218:221] offset:640
	ds_write_b128 v236, v[222:225] offset:704
	s_mov_b64 exec, -1
	s_waitcnt lgkmcnt(0)
	s_add_u32 s0, s0, 0x2000
	s_addc_u32 s1, s1, 0
	s_lshr_b32 s57, s48, 17
	s_add_u32 s57, s57, 5
	s_mul_i32 s57, s57, 0x6000
	s_add_u32 s2, s2, s57
	s_addc_u32 s3, s3, 0
	s_add_u32 s36, s2, 0x2000
	s_addc_u32 s37, s3, 0
	s_add_u32 s94, s94, 0x100000
	s_addc_u32 s95, s95, 0
	s_movk_i32 s45, 16
	s_barrier
	s_cmp_lt_u32 s32, 0x100
	s_cbranch_scc0 .Lgo_p2_w1
	v_lshlrev_b32_e32 v238, 2, v167
	v_add_u32_e32 v239, 0x21000, v238
	ds_read_b32 v240, v239
	ds_read_b32 v241, v239 offset:1024
	ds_read_b32 v242, v239 offset:2048
	ds_read_b32 v243, v239 offset:3072
	v_add_u32_e32 v244, s48, v238
	s_waitcnt lgkmcnt(0)
	v_add_f32_e32 v240, v240, v241
	v_add_f32_e32 v240, v240, v242
	v_add_f32_e32 v240, v240, v243
	global_store_dword v244, v240, s[94:95] sc0 sc1
	s_waitcnt vmcnt(0)
.Lgo_p2_w1:
	global_load_dword v128, v237, s[0:1]
	global_load_dword v132, v237, s[2:3]
	global_load_dword v136, v237, s[36:37]
	global_load_dword v129, v237, s[0:1] offset:64
	global_load_dword v133, v237, s[2:3] offset:64
	global_load_dword v137, v237, s[36:37] offset:64
	global_load_dword v130, v237, s[0:1] offset:512
	global_load_dword v134, v237, s[2:3] offset:512
	global_load_dword v138, v237, s[36:37] offset:512
	global_load_dword v131, v237, s[0:1] offset:576
	global_load_dword v135, v237, s[2:3] offset:576
	global_load_dword v139, v237, s[36:37] offset:576
	s_barrier
	s_cmp_lt_u32 s32, 64
	s_cbranch_scc0 .Lgo_p2_w2
	v_mov_b32_e32 v245, v234
	v_mov_b32_e32 v246, 1
	s_mov_b64 exec, 1
	global_atomic_add v245, v246, s[98:99]
	s_mov_b32 s57, 0

.Lgo_p2_got:
	s_mov_b64 exec, -1
	buffer_inv sc1
.Lgo_p2_w2:
	s_barrier
	s_cmp_lt_u32 s32, 0x100
	s_cbranch_scc0 .Lgo_p2_w3
	v_mov_b32_e32 v244, v235
	v_add_u32_e32 v245, 0x1000, v244
	global_load_dword v246, v244, s[94:95] sc0 sc1
	global_load_dword v247, v244, s[94:95] offset:1024 sc0 sc1
	global_load_dword v248, v244, s[94:95] offset:2048 sc0 sc1
	global_load_dword v249, v244, s[94:95] offset:3072 sc0 sc1
	global_load_dword v250, v245, s[94:95] sc0 sc1
	global_load_dword v251, v245, s[94:95] offset:1024 sc0 sc1
	global_load_dword v252, v245, s[94:95] offset:2048 sc0 sc1
	global_load_dword v253, v245, s[94:95] offset:3072 sc0 sc1
	s_waitcnt vmcnt(0)
	v_add_f32_e32 v246, v246, v247
	v_add_f32_e32 v246, v246, v248
	v_add_f32_e32 v246, v246, v249
	v_add_f32_e32 v246, v246, v250
	v_add_f32_e32 v246, v246, v251
	v_add_f32_e32 v246, v246, v252
	v_add_f32_e32 v246, v246, v253
	v_fmamk_f32 v246, v246, 0x3a000000, v166
	v_mul_f32_e32 v247, 0x4b800000, v246
	v_cmp_gt_f32_e32 vcc, s58, v246
	s_nop 1
	v_cndmask_b32_e32 v246, v246, v247, vcc
	v_rsq_f32_e32 v248, v246
	s_nop 0
	v_mul_f32_e32 v247, 0x45800000, v248
	v_cndmask_b32_e32 v248, v248, v247, vcc
	ds_write_b32 v239, v248
	s_waitcnt lgkmcnt(0)
.Lgo_p2_w3:
	s_barrier
	v_lshlrev_b32_e32 v236, 2, v163
	v_add_u32_e32 v236, 0x21000, v236
	ds_read_b128 v[194:197], v236
	ds_read_b128 v[198:201], v236 offset:64
	ds_read_b128 v[202:205], v236 offset:128
	ds_read_b128 v[206:209], v236 offset:192
	ds_read_b128 v[210:213], v236 offset:512
	ds_read_b128 v[214:217], v236 offset:576
	ds_read_b128 v[218:221], v236 offset:640
	ds_read_b128 v[222:225], v236 offset:704
	s_lshr_b32 s57, s48, 13
	s_lshl_b32 s57, s57, 8
	v_add_u32_e32 v172, s57, v163
	v_lshlrev_b32_e32 v172, 12, v172
	v_lshrrev_b32_e32 v173, 1, v237
	v_add_u32_e32 v172, v172, v173
	v_and_b32_e32 v173, 1, v160
	v_mul_u32_u24_e32 v174, 30, v173
	v_add_u32_e32 v172, v172, v174
	v_cmp_eq_u32_e32 vcc, 1, v173
	v_add_u32_e32 v173, 0x1000, v172
	v_add_u32_e32 v174, 0x2000, v172
	v_add_u32_e32 v175, 0x3000, v172
	s_waitcnt vmcnt(0) lgkmcnt(0)
	v_add_f32_e32 v136, 1.0, v136
	v_add_f32_e32 v137, 1.0, v137
	v_add_f32_e32 v138, 1.0, v138
	v_add_f32_e32 v139, 1.0, v139
	v_mov_b32_e32 v176, v172
	v_mov_b32_e32 v177, v173
	v_mov_b32_e32 v178, v174
	v_mov_b32_e32 v179, v175
	v_mul_f32_e32 v124, v124, v194
	v_mul_f32_e32 v124, v128, v124
	v_fma_f32 v124, v136, v124, v132
	v_mul_f32_e32 v120, v120, v194
	v_mul_f32_e32 v120, v129, v120
	v_fma_f32 v120, v137, v120, v133
	v_mul_f32_e32 v100, v100, v194
	v_mul_f32_e32 v100, v130, v100
	v_fma_f32 v100, v138, v100, v134
	v_mul_f32_e32 v96, v96, v194
	v_mul_f32_e32 v96, v131, v96
	v_fma_f32 v96, v139, v96, v135
	v_cndmask_b32_e32 v140, v120, v124, vcc
	v_cndmask_b32_e32 v144, v96, v100, vcc
	s_nop 0
	v_mov_b32_dpp v141, v140 quad_perm:[1,0,3,2] row_mask:0xf bank_mask:0xf
	v_mov_b32_dpp v145, v144 quad_perm:[1,0,3,2] row_mask:0xf bank_mask:0xf
	s_nop 0
	v_cndmask_b32_e32 v142, v124, v141, vcc
	v_cndmask_b32_e32 v143, v141, v120, vcc
	v_cndmask_b32_e32 v146, v100, v145, vcc
	v_cndmask_b32_e32 v147, v145, v96, vcc
	v_cvt_pk_bf16_f32 v148, v142, v143
	global_store_dword v176, v148, s[34:35]
	v_cvt_pk_bf16_f32 v149, v146, v147
	global_store_dword v176, v149, s[34:35] offset:256
	v_mul_f32_e32 v125, v125, v195
	v_mul_f32_e32 v125, v128, v125
	v_fma_f32 v125, v136, v125, v132
	v_mul_f32_e32 v121, v121, v195
	v_mul_f32_e32 v121, v129, v121
	v_fma_f32 v121, v137, v121, v133
	v_mul_f32_e32 v101, v101, v195
	v_mul_f32_e32 v101, v130, v101
	v_fma_f32 v101, v138, v101, v134
	v_mul_f32_e32 v97, v97, v195
	v_mul_f32_e32 v97, v131, v97
	v_fma_f32 v97, v139, v97, v135
	v_cndmask_b32_e32 v140, v121, v125, vcc
	v_cndmask_b32_e32 v144, v97, v101, vcc
	s_nop 0
	v_mov_b32_dpp v141, v140 quad_perm:[1,0,3,2] row_mask:0xf bank_mask:0xf
	v_mov_b32_dpp v145, v144 quad_perm:[1,0,3,2] row_mask:0xf bank_mask:0xf
	s_nop 0
	v_cndmask_b32_e32 v142, v125, v141, vcc
	v_cndmask_b32_e32 v143, v141, v121, vcc
	v_cndmask_b32_e32 v146, v101, v145, vcc
	v_cndmask_b32_e32 v147, v145, v97, vcc
	v_cvt_pk_bf16_f32 v150, v142, v143
	global_store_dword v177, v150, s[34:35]
	v_cvt_pk_bf16_f32 v151, v146, v147
	global_store_dword v177, v151, s[34:35] offset:256
	v_mul_f32_e32 v126, v126, v196
	v_mul_f32_e32 v126, v128, v126
	v_fma_f32 v126, v136, v126, v132
	v_mul_f32_e32 v122, v122, v196
	v_mul_f32_e32 v122, v129, v122
	v_fma_f32 v122, v137, v122, v133
	v_mul_f32_e32 v102, v102, v196
	v_mul_f32_e32 v102, v130, v102
	v_fma_f32 v102, v138, v102, v134
	v_mul_f32_e32 v98, v98, v196
	v_mul_f32_e32 v98, v131, v98
	v_fma_f32 v98, v139, v98, v135
	v_cndmask_b32_e32 v140, v122, v126, vcc
	v_cndmask_b32_e32 v144, v98, v102, vcc
	s_nop 0
	v_mov_b32_dpp v141, v140 quad_perm:[1,0,3,2] row_mask:0xf bank_mask:0xf
	v_mov_b32_dpp v145, v144 quad_perm:[1,0,3,2] row_mask:0xf bank_mask:0xf
	s_nop 0
	v_cndmask_b32_e32 v142, v126, v141, vcc
	v_cndmask_b32_e32 v143, v141, v122, vcc
	v_cndmask_b32_e32 v146, v102, v145, vcc
	v_cndmask_b32_e32 v147, v145, v98, vcc
	v_cvt_pk_bf16_f32 v152, v142, v143
	global_store_dword v178, v152, s[34:35]
	v_cvt_pk_bf16_f32 v153, v146, v147
	global_store_dword v178, v153, s[34:35] offset:256
	v_mul_f32_e32 v127, v127, v197
	v_mul_f32_e32 v127, v128, v127
	v_fma_f32 v127, v136, v127, v132
	v_mul_f32_e32 v123, v123, v197
	v_mul_f32_e32 v123, v129, v123
	v_fma_f32 v123, v137, v123, v133
	v_mul_f32_e32 v103, v103, v197
	v_mul_f32_e32 v103, v130, v103
	v_fma_f32 v103, v138, v103, v134
	v_mul_f32_e32 v99, v99, v197
	v_mul_f32_e32 v99, v131, v99
	v_fma_f32 v99, v139, v99, v135
	v_cndmask_b32_e32 v140, v123, v127, vcc
	v_cndmask_b32_e32 v144, v99, v103, vcc
	s_nop 0
	v_mov_b32_dpp v141, v140 quad_perm:[1,0,3,2] row_mask:0xf bank_mask:0xf
	v_mov_b32_dpp v145, v144 quad_perm:[1,0,3,2] row_mask:0xf bank_mask:0xf
	s_nop 0
	v_cndmask_b32_e32 v142, v127, v141, vcc
	v_cndmask_b32_e32 v143, v141, v123, vcc
	v_cndmask_b32_e32 v146, v103, v145, vcc
	v_cndmask_b32_e32 v147, v145, v99, vcc
	v_cvt_pk_bf16_f32 v154, v142, v143
	global_store_dword v179, v154, s[34:35]
	v_cvt_pk_bf16_f32 v155, v146, v147
	global_store_dword v179, v155, s[34:35] offset:256
	v_add_u32_e32 v176, 0x10000, v172
	v_add_u32_e32 v177, 0x10000, v173
	v_add_u32_e32 v178, 0x10000, v174
	v_add_u32_e32 v179, 0x10000, v175
	v_mul_f32_e32 v116, v116, v198
	v_mul_f32_e32 v116, v128, v116
	v_fma_f32 v116, v136, v116, v132
	v_mul_f32_e32 v112, v112, v198
	v_mul_f32_e32 v112, v129, v112
	v_fma_f32 v112, v137, v112, v133
	v_mul_f32_e32 v92, v92, v198
	v_mul_f32_e32 v92, v130, v92
	v_fma_f32 v92, v138, v92, v134
	v_mul_f32_e32 v88, v88, v198
	v_mul_f32_e32 v88, v131, v88
	v_fma_f32 v88, v139, v88, v135
	v_cndmask_b32_e32 v140, v112, v116, vcc
	v_cndmask_b32_e32 v144, v88, v92, vcc
	s_nop 0
	v_mov_b32_dpp v141, v140 quad_perm:[1,0,3,2] row_mask:0xf bank_mask:0xf
	v_mov_b32_dpp v145, v144 quad_perm:[1,0,3,2] row_mask:0xf bank_mask:0xf
	s_nop 0
	v_cndmask_b32_e32 v142, v116, v141, vcc
	v_cndmask_b32_e32 v143, v141, v112, vcc
	v_cndmask_b32_e32 v146, v92, v145, vcc
	v_cndmask_b32_e32 v147, v145, v88, vcc
	v_cvt_pk_bf16_f32 v148, v142, v143
	global_store_dword v176, v148, s[34:35]
	v_cvt_pk_bf16_f32 v149, v146, v147
	global_store_dword v176, v149, s[34:35] offset:256
	v_mul_f32_e32 v117, v117, v199
	v_mul_f32_e32 v117, v128, v117
	v_fma_f32 v117, v136, v117, v132
	v_mul_f32_e32 v113, v113, v199
	v_mul_f32_e32 v113, v129, v113
	v_fma_f32 v113, v137, v113, v133
	v_mul_f32_e32 v93, v93, v199
	v_mul_f32_e32 v93, v130, v93
	v_fma_f32 v93, v138, v93, v134
	v_mul_f32_e32 v89, v89, v199
	v_mul_f32_e32 v89, v131, v89
	v_fma_f32 v89, v139, v89, v135
	v_cndmask_b32_e32 v140, v113, v117, vcc
	v_cndmask_b32_e32 v144, v89, v93, vcc
	s_nop 0
	v_mov_b32_dpp v141, v140 quad_perm:[1,0,3,2] row_mask:0xf bank_mask:0xf
	v_mov_b32_dpp v145, v144 quad_perm:[1,0,3,2] row_mask:0xf bank_mask:0xf
	s_nop 0
	v_cndmask_b32_e32 v142, v117, v141, vcc
	v_cndmask_b32_e32 v143, v141, v113, vcc
	v_cndmask_b32_e32 v146, v93, v145, vcc
	v_cndmask_b32_e32 v147, v145, v89, vcc
	v_cvt_pk_bf16_f32 v150, v142, v143
	global_store_dword v177, v150, s[34:35]
	v_cvt_pk_bf16_f32 v151, v146, v147
	global_store_dword v177, v151, s[34:35] offset:256
	v_mul_f32_e32 v118, v118, v200
	v_mul_f32_e32 v118, v128, v118
	v_fma_f32 v118, v136, v118, v132
	v_mul_f32_e32 v114, v114, v200
	v_mul_f32_e32 v114, v129, v114
	v_fma_f32 v114, v137, v114, v133
	v_mul_f32_e32 v94, v94, v200
	v_mul_f32_e32 v94, v130, v94
	v_fma_f32 v94, v138, v94, v134
	v_mul_f32_e32 v90, v90, v200
	v_mul_f32_e32 v90, v131, v90
	v_fma_f32 v90, v139, v90, v135
	v_cndmask_b32_e32 v140, v114, v118, vcc
	v_cndmask_b32_e32 v144, v90, v94, vcc
	s_nop 0
	v_mov_b32_dpp v141, v140 quad_perm:[1,0,3,2] row_mask:0xf bank_mask:0xf
	v_mov_b32_dpp v145, v144 quad_perm:[1,0,3,2] row_mask:0xf bank_mask:0xf
	s_nop 0
	v_cndmask_b32_e32 v142, v118, v141, vcc
	v_cndmask_b32_e32 v143, v141, v114, vcc
	v_cndmask_b32_e32 v146, v94, v145, vcc
	v_cndmask_b32_e32 v147, v145, v90, vcc
	v_cvt_pk_bf16_f32 v152, v142, v143
	global_store_dword v178, v152, s[34:35]
	v_cvt_pk_bf16_f32 v153, v146, v147
	global_store_dword v178, v153, s[34:35] offset:256
	v_mul_f32_e32 v119, v119, v201
	v_mul_f32_e32 v119, v128, v119
	v_fma_f32 v119, v136, v119, v132
	v_mul_f32_e32 v115, v115, v201
	v_mul_f32_e32 v115, v129, v115
	v_fma_f32 v115, v137, v115, v133
	v_mul_f32_e32 v95, v95, v201
	v_mul_f32_e32 v95, v130, v95
	v_fma_f32 v95, v138, v95, v134
	v_mul_f32_e32 v91, v91, v201
	v_mul_f32_e32 v91, v131, v91
	v_fma_f32 v91, v139, v91, v135
	v_cndmask_b32_e32 v140, v115, v119, vcc
	v_cndmask_b32_e32 v144, v91, v95, vcc
	s_nop 0
	v_mov_b32_dpp v141, v140 quad_perm:[1,0,3,2] row_mask:0xf bank_mask:0xf
	v_mov_b32_dpp v145, v144 quad_perm:[1,0,3,2] row_mask:0xf bank_mask:0xf
	s_nop 0
	v_cndmask_b32_e32 v142, v119, v141, vcc
	v_cndmask_b32_e32 v143, v141, v115, vcc
	v_cndmask_b32_e32 v146, v95, v145, vcc
	v_cndmask_b32_e32 v147, v145, v91, vcc
	v_cvt_pk_bf16_f32 v154, v142, v143
	global_store_dword v179, v154, s[34:35]
	v_cvt_pk_bf16_f32 v155, v146, v147
	global_store_dword v179, v155, s[34:35] offset:256
	v_add_u32_e32 v176, 0x20000, v172
	v_add_u32_e32 v177, 0x20000, v173
	v_add_u32_e32 v178, 0x20000, v174
	v_add_u32_e32 v179, 0x20000, v175
	v_mul_f32_e32 v108, v108, v202
	v_mul_f32_e32 v108, v128, v108
	v_fma_f32 v108, v136, v108, v132
	v_mul_f32_e32 v104, v104, v202
	v_mul_f32_e32 v104, v129, v104
	v_fma_f32 v104, v137, v104, v133
	v_mul_f32_e32 v80, v80, v202
	v_mul_f32_e32 v80, v130, v80
	v_fma_f32 v80, v138, v80, v134
	v_mul_f32_e32 v72, v72, v202
	v_mul_f32_e32 v72, v131, v72
	v_fma_f32 v72, v139, v72, v135
	v_cndmask_b32_e32 v140, v104, v108, vcc
	v_cndmask_b32_e32 v144, v72, v80, vcc
	s_nop 0
	v_mov_b32_dpp v141, v140 quad_perm:[1,0,3,2] row_mask:0xf bank_mask:0xf
	v_mov_b32_dpp v145, v144 quad_perm:[1,0,3,2] row_mask:0xf bank_mask:0xf
	s_nop 0
	v_cndmask_b32_e32 v142, v108, v141, vcc
	v_cndmask_b32_e32 v143, v141, v104, vcc
	v_cndmask_b32_e32 v146, v80, v145, vcc
	v_cndmask_b32_e32 v147, v145, v72, vcc
	v_cvt_pk_bf16_f32 v148, v142, v143
	global_store_dword v176, v148, s[34:35]
	v_cvt_pk_bf16_f32 v149, v146, v147
	global_store_dword v176, v149, s[34:35] offset:256
	v_mul_f32_e32 v109, v109, v203
	v_mul_f32_e32 v109, v128, v109
	v_fma_f32 v109, v136, v109, v132
	v_mul_f32_e32 v105, v105, v203
	v_mul_f32_e32 v105, v129, v105
	v_fma_f32 v105, v137, v105, v133
	v_mul_f32_e32 v81, v81, v203
	v_mul_f32_e32 v81, v130, v81
	v_fma_f32 v81, v138, v81, v134
	v_mul_f32_e32 v73, v73, v203
	v_mul_f32_e32 v73, v131, v73
	v_fma_f32 v73, v139, v73, v135
	v_cndmask_b32_e32 v140, v105, v109, vcc
	v_cndmask_b32_e32 v144, v73, v81, vcc
	s_nop 0
	v_mov_b32_dpp v141, v140 quad_perm:[1,0,3,2] row_mask:0xf bank_mask:0xf
	v_mov_b32_dpp v145, v144 quad_perm:[1,0,3,2] row_mask:0xf bank_mask:0xf
	s_nop 0
	v_cndmask_b32_e32 v142, v109, v141, vcc
	v_cndmask_b32_e32 v143, v141, v105, vcc
	v_cndmask_b32_e32 v146, v81, v145, vcc
	v_cndmask_b32_e32 v147, v145, v73, vcc
	v_cvt_pk_bf16_f32 v150, v142, v143
	global_store_dword v177, v150, s[34:35]
	v_cvt_pk_bf16_f32 v151, v146, v147
	global_store_dword v177, v151, s[34:35] offset:256
	v_mul_f32_e32 v110, v110, v204
	v_mul_f32_e32 v110, v128, v110
	v_fma_f32 v110, v136, v110, v132
	v_mul_f32_e32 v106, v106, v204
	v_mul_f32_e32 v106, v129, v106
	v_fma_f32 v106, v137, v106, v133
	v_mul_f32_e32 v82, v82, v204
	v_mul_f32_e32 v82, v130, v82
	v_fma_f32 v82, v138, v82, v134
	v_mul_f32_e32 v74, v74, v204
	v_mul_f32_e32 v74, v131, v74
	v_fma_f32 v74, v139, v74, v135
	v_cndmask_b32_e32 v140, v106, v110, vcc
	v_cndmask_b32_e32 v144, v74, v82, vcc
	s_nop 0
	v_mov_b32_dpp v141, v140 quad_perm:[1,0,3,2] row_mask:0xf bank_mask:0xf
	v_mov_b32_dpp v145, v144 quad_perm:[1,0,3,2] row_mask:0xf bank_mask:0xf
	s_nop 0
	v_cndmask_b32_e32 v142, v110, v141, vcc
	v_cndmask_b32_e32 v143, v141, v106, vcc
	v_cndmask_b32_e32 v146, v82, v145, vcc
	v_cndmask_b32_e32 v147, v145, v74, vcc
	v_cvt_pk_bf16_f32 v152, v142, v143
	global_store_dword v178, v152, s[34:35]
	v_cvt_pk_bf16_f32 v153, v146, v147
	global_store_dword v178, v153, s[34:35] offset:256
	v_mul_f32_e32 v111, v111, v205
	v_mul_f32_e32 v111, v128, v111
	v_fma_f32 v111, v136, v111, v132
	v_mul_f32_e32 v107, v107, v205
	v_mul_f32_e32 v107, v129, v107
	v_fma_f32 v107, v137, v107, v133
	v_mul_f32_e32 v83, v83, v205
	v_mul_f32_e32 v83, v130, v83
	v_fma_f32 v83, v138, v83, v134
	v_mul_f32_e32 v75, v75, v205
	v_mul_f32_e32 v75, v131, v75
	v_fma_f32 v75, v139, v75, v135
	v_cndmask_b32_e32 v140, v107, v111, vcc
	v_cndmask_b32_e32 v144, v75, v83, vcc
	s_nop 0
	v_mov_b32_dpp v141, v140 quad_perm:[1,0,3,2] row_mask:0xf bank_mask:0xf
	v_mov_b32_dpp v145, v144 quad_perm:[1,0,3,2] row_mask:0xf bank_mask:0xf
	s_nop 0
	v_cndmask_b32_e32 v142, v111, v141, vcc
	v_cndmask_b32_e32 v143, v141, v107, vcc
	v_cndmask_b32_e32 v146, v83, v145, vcc
	v_cndmask_b32_e32 v147, v145, v75, vcc
	v_cvt_pk_bf16_f32 v154, v142, v143
	global_store_dword v179, v154, s[34:35]
	v_cvt_pk_bf16_f32 v155, v146, v147
	global_store_dword v179, v155, s[34:35] offset:256
	v_add_u32_e32 v176, 0x30000, v172
	v_add_u32_e32 v177, 0x30000, v173
	v_add_u32_e32 v178, 0x30000, v174
	v_add_u32_e32 v179, 0x30000, v175
	v_mul_f32_e32 v84, v84, v206
	v_mul_f32_e32 v84, v128, v84
	v_fma_f32 v84, v136, v84, v132
	v_mul_f32_e32 v76, v76, v206
	v_mul_f32_e32 v76, v129, v76
	v_fma_f32 v76, v137, v76, v133
	v_mul_f32_e32 v68, v68, v206
	v_mul_f32_e32 v68, v130, v68
	v_fma_f32 v68, v138, v68, v134
	v_mul_f32_e32 v64, v64, v206
	v_mul_f32_e32 v64, v131, v64
	v_fma_f32 v64, v139, v64, v135
	v_cndmask_b32_e32 v140, v76, v84, vcc
	v_cndmask_b32_e32 v144, v64, v68, vcc
	s_nop 0
	v_mov_b32_dpp v141, v140 quad_perm:[1,0,3,2] row_mask:0xf bank_mask:0xf
	v_mov_b32_dpp v145, v144 quad_perm:[1,0,3,2] row_mask:0xf bank_mask:0xf
	s_nop 0
	v_cndmask_b32_e32 v142, v84, v141, vcc
	v_cndmask_b32_e32 v143, v141, v76, vcc
	v_cndmask_b32_e32 v146, v68, v145, vcc
	v_cndmask_b32_e32 v147, v145, v64, vcc
	v_cvt_pk_bf16_f32 v148, v142, v143
	global_store_dword v176, v148, s[34:35]
	v_cvt_pk_bf16_f32 v149, v146, v147
	global_store_dword v176, v149, s[34:35] offset:256
	v_mul_f32_e32 v85, v85, v207
	v_mul_f32_e32 v85, v128, v85
	v_fma_f32 v85, v136, v85, v132
	v_mul_f32_e32 v77, v77, v207
	v_mul_f32_e32 v77, v129, v77
	v_fma_f32 v77, v137, v77, v133
	v_mul_f32_e32 v69, v69, v207
	v_mul_f32_e32 v69, v130, v69
	v_fma_f32 v69, v138, v69, v134
	v_mul_f32_e32 v65, v65, v207
	v_mul_f32_e32 v65, v131, v65
	v_fma_f32 v65, v139, v65, v135
	v_cndmask_b32_e32 v140, v77, v85, vcc
	v_cndmask_b32_e32 v144, v65, v69, vcc
	s_nop 0
	v_mov_b32_dpp v141, v140 quad_perm:[1,0,3,2] row_mask:0xf bank_mask:0xf
	v_mov_b32_dpp v145, v144 quad_perm:[1,0,3,2] row_mask:0xf bank_mask:0xf
	s_nop 0
	v_cndmask_b32_e32 v142, v85, v141, vcc
	v_cndmask_b32_e32 v143, v141, v77, vcc
	v_cndmask_b32_e32 v146, v69, v145, vcc
	v_cndmask_b32_e32 v147, v145, v65, vcc
	v_cvt_pk_bf16_f32 v150, v142, v143
	global_store_dword v177, v150, s[34:35]
	v_cvt_pk_bf16_f32 v151, v146, v147
	global_store_dword v177, v151, s[34:35] offset:256
	v_mul_f32_e32 v86, v86, v208
	v_mul_f32_e32 v86, v128, v86
	v_fma_f32 v86, v136, v86, v132
	v_mul_f32_e32 v78, v78, v208
	v_mul_f32_e32 v78, v129, v78
	v_fma_f32 v78, v137, v78, v133
	v_mul_f32_e32 v70, v70, v208
	v_mul_f32_e32 v70, v130, v70
	v_fma_f32 v70, v138, v70, v134
	v_mul_f32_e32 v66, v66, v208
	v_mul_f32_e32 v66, v131, v66
	v_fma_f32 v66, v139, v66, v135
	v_cndmask_b32_e32 v140, v78, v86, vcc
	v_cndmask_b32_e32 v144, v66, v70, vcc
	s_nop 0
	v_mov_b32_dpp v141, v140 quad_perm:[1,0,3,2] row_mask:0xf bank_mask:0xf
	v_mov_b32_dpp v145, v144 quad_perm:[1,0,3,2] row_mask:0xf bank_mask:0xf
	s_nop 0
	v_cndmask_b32_e32 v142, v86, v141, vcc
	v_cndmask_b32_e32 v143, v141, v78, vcc
	v_cndmask_b32_e32 v146, v70, v145, vcc
	v_cndmask_b32_e32 v147, v145, v66, vcc
	v_cvt_pk_bf16_f32 v152, v142, v143
	global_store_dword v178, v152, s[34:35]
	v_cvt_pk_bf16_f32 v153, v146, v147
	global_store_dword v178, v153, s[34:35] offset:256
	v_mul_f32_e32 v87, v87, v209
	v_mul_f32_e32 v87, v128, v87
	v_fma_f32 v87, v136, v87, v132
	v_mul_f32_e32 v79, v79, v209
	v_mul_f32_e32 v79, v129, v79
	v_fma_f32 v79, v137, v79, v133
	v_mul_f32_e32 v71, v71, v209
	v_mul_f32_e32 v71, v130, v71
	v_fma_f32 v71, v138, v71, v134
	v_mul_f32_e32 v67, v67, v209
	v_mul_f32_e32 v67, v131, v67
	v_fma_f32 v67, v139, v67, v135
	v_cndmask_b32_e32 v140, v79, v87, vcc
	v_cndmask_b32_e32 v144, v67, v71, vcc
	s_nop 0
	v_mov_b32_dpp v141, v140 quad_perm:[1,0,3,2] row_mask:0xf bank_mask:0xf
	v_mov_b32_dpp v145, v144 quad_perm:[1,0,3,2] row_mask:0xf bank_mask:0xf
	s_nop 0
	v_cndmask_b32_e32 v142, v87, v141, vcc
	v_cndmask_b32_e32 v143, v141, v79, vcc
	v_cndmask_b32_e32 v146, v71, v145, vcc
	v_cndmask_b32_e32 v147, v145, v67, vcc
	v_cvt_pk_bf16_f32 v154, v142, v143
	global_store_dword v179, v154, s[34:35]
	v_cvt_pk_bf16_f32 v155, v146, v147
	global_store_dword v179, v155, s[34:35] offset:256
	v_add_u32_e32 v176, 0x80000, v172
	v_add_u32_e32 v177, 0x80000, v173
	v_add_u32_e32 v178, 0x80000, v174
	v_add_u32_e32 v179, 0x80000, v175
	v_mul_f32_e32 v60, v60, v210
	v_mul_f32_e32 v60, v128, v60
	v_fma_f32 v60, v136, v60, v132
	v_mul_f32_e32 v56, v56, v210
	v_mul_f32_e32 v56, v129, v56
	v_fma_f32 v56, v137, v56, v133
	v_mul_f32_e32 v32, v32, v210
	v_mul_f32_e32 v32, v130, v32
	v_fma_f32 v32, v138, v32, v134
	v_mul_f32_e32 v24, v24, v210
	v_mul_f32_e32 v24, v131, v24
	v_fma_f32 v24, v139, v24, v135
	v_cndmask_b32_e32 v140, v56, v60, vcc
	v_cndmask_b32_e32 v144, v24, v32, vcc
	s_nop 0
	v_mov_b32_dpp v141, v140 quad_perm:[1,0,3,2] row_mask:0xf bank_mask:0xf
	v_mov_b32_dpp v145, v144 quad_perm:[1,0,3,2] row_mask:0xf bank_mask:0xf
	s_nop 0
	v_cndmask_b32_e32 v142, v60, v141, vcc
	v_cndmask_b32_e32 v143, v141, v56, vcc
	v_cndmask_b32_e32 v146, v32, v145, vcc
	v_cndmask_b32_e32 v147, v145, v24, vcc
	v_cvt_pk_bf16_f32 v148, v142, v143
	global_store_dword v176, v148, s[34:35]
	v_cvt_pk_bf16_f32 v149, v146, v147
	global_store_dword v176, v149, s[34:35] offset:256
	v_mul_f32_e32 v61, v61, v211
	v_mul_f32_e32 v61, v128, v61
	v_fma_f32 v61, v136, v61, v132
	v_mul_f32_e32 v57, v57, v211
	v_mul_f32_e32 v57, v129, v57
	v_fma_f32 v57, v137, v57, v133
	v_mul_f32_e32 v33, v33, v211
	v_mul_f32_e32 v33, v130, v33
	v_fma_f32 v33, v138, v33, v134
	v_mul_f32_e32 v25, v25, v211
	v_mul_f32_e32 v25, v131, v25
	v_fma_f32 v25, v139, v25, v135
	v_cndmask_b32_e32 v140, v57, v61, vcc
	v_cndmask_b32_e32 v144, v25, v33, vcc
	s_nop 0
	v_mov_b32_dpp v141, v140 quad_perm:[1,0,3,2] row_mask:0xf bank_mask:0xf
	v_mov_b32_dpp v145, v144 quad_perm:[1,0,3,2] row_mask:0xf bank_mask:0xf
	s_nop 0
	v_cndmask_b32_e32 v142, v61, v141, vcc
	v_cndmask_b32_e32 v143, v141, v57, vcc
	v_cndmask_b32_e32 v146, v33, v145, vcc
	v_cndmask_b32_e32 v147, v145, v25, vcc
	v_cvt_pk_bf16_f32 v150, v142, v143
	global_store_dword v177, v150, s[34:35]
	v_cvt_pk_bf16_f32 v151, v146, v147
	global_store_dword v177, v151, s[34:35] offset:256
	v_mul_f32_e32 v62, v62, v212
	v_mul_f32_e32 v62, v128, v62
	v_fma_f32 v62, v136, v62, v132
	v_mul_f32_e32 v58, v58, v212
	v_mul_f32_e32 v58, v129, v58
	v_fma_f32 v58, v137, v58, v133
	v_mul_f32_e32 v34, v34, v212
	v_mul_f32_e32 v34, v130, v34
	v_fma_f32 v34, v138, v34, v134
	v_mul_f32_e32 v26, v26, v212
	v_mul_f32_e32 v26, v131, v26
	v_fma_f32 v26, v139, v26, v135
	v_cndmask_b32_e32 v140, v58, v62, vcc
	v_cndmask_b32_e32 v144, v26, v34, vcc
	s_nop 0
	v_mov_b32_dpp v141, v140 quad_perm:[1,0,3,2] row_mask:0xf bank_mask:0xf
	v_mov_b32_dpp v145, v144 quad_perm:[1,0,3,2] row_mask:0xf bank_mask:0xf
	s_nop 0
	v_cndmask_b32_e32 v142, v62, v141, vcc
	v_cndmask_b32_e32 v143, v141, v58, vcc
	v_cndmask_b32_e32 v146, v34, v145, vcc
	v_cndmask_b32_e32 v147, v145, v26, vcc
	v_cvt_pk_bf16_f32 v152, v142, v143
	global_store_dword v178, v152, s[34:35]
	v_cvt_pk_bf16_f32 v153, v146, v147
	global_store_dword v178, v153, s[34:35] offset:256
	v_mul_f32_e32 v63, v63, v213
	v_mul_f32_e32 v63, v128, v63
	v_fma_f32 v63, v136, v63, v132
	v_mul_f32_e32 v59, v59, v213
	v_mul_f32_e32 v59, v129, v59
	v_fma_f32 v59, v137, v59, v133
	v_mul_f32_e32 v35, v35, v213
	v_mul_f32_e32 v35, v130, v35
	v_fma_f32 v35, v138, v35, v134
	v_mul_f32_e32 v27, v27, v213
	v_mul_f32_e32 v27, v131, v27
	v_fma_f32 v27, v139, v27, v135
	v_cndmask_b32_e32 v140, v59, v63, vcc
	v_cndmask_b32_e32 v144, v27, v35, vcc
	s_nop 0
	v_mov_b32_dpp v141, v140 quad_perm:[1,0,3,2] row_mask:0xf bank_mask:0xf
	v_mov_b32_dpp v145, v144 quad_perm:[1,0,3,2] row_mask:0xf bank_mask:0xf
	s_nop 0
	v_cndmask_b32_e32 v142, v63, v141, vcc
	v_cndmask_b32_e32 v143, v141, v59, vcc
	v_cndmask_b32_e32 v146, v35, v145, vcc
	v_cndmask_b32_e32 v147, v145, v27, vcc
	v_cvt_pk_bf16_f32 v154, v142, v143
	global_store_dword v179, v154, s[34:35]
	v_cvt_pk_bf16_f32 v155, v146, v147
	global_store_dword v179, v155, s[34:35] offset:256
	v_add_u32_e32 v176, 0x90000, v172
	v_add_u32_e32 v177, 0x90000, v173
	v_add_u32_e32 v178, 0x90000, v174
	v_add_u32_e32 v179, 0x90000, v175
	v_mul_f32_e32 v52, v52, v214
	v_mul_f32_e32 v52, v128, v52
	v_fma_f32 v52, v136, v52, v132
	v_mul_f32_e32 v48, v48, v214
	v_mul_f32_e32 v48, v129, v48
	v_fma_f32 v48, v137, v48, v133
	v_mul_f32_e32 v20, v20, v214
	v_mul_f32_e32 v20, v130, v20
	v_fma_f32 v20, v138, v20, v134
	v_mul_f32_e32 v16, v16, v214
	v_mul_f32_e32 v16, v131, v16
	v_fma_f32 v16, v139, v16, v135
	v_cndmask_b32_e32 v140, v48, v52, vcc
	v_cndmask_b32_e32 v144, v16, v20, vcc
	s_nop 0
	v_mov_b32_dpp v141, v140 quad_perm:[1,0,3,2] row_mask:0xf bank_mask:0xf
	v_mov_b32_dpp v145, v144 quad_perm:[1,0,3,2] row_mask:0xf bank_mask:0xf
	s_nop 0
	v_cndmask_b32_e32 v142, v52, v141, vcc
	v_cndmask_b32_e32 v143, v141, v48, vcc
	v_cndmask_b32_e32 v146, v20, v145, vcc
	v_cndmask_b32_e32 v147, v145, v16, vcc
	v_cvt_pk_bf16_f32 v148, v142, v143
	global_store_dword v176, v148, s[34:35]
	v_cvt_pk_bf16_f32 v149, v146, v147
	global_store_dword v176, v149, s[34:35] offset:256
	v_mul_f32_e32 v53, v53, v215
	v_mul_f32_e32 v53, v128, v53
	v_fma_f32 v53, v136, v53, v132
	v_mul_f32_e32 v49, v49, v215
	v_mul_f32_e32 v49, v129, v49
	v_fma_f32 v49, v137, v49, v133
	v_mul_f32_e32 v21, v21, v215
	v_mul_f32_e32 v21, v130, v21
	v_fma_f32 v21, v138, v21, v134
	v_mul_f32_e32 v17, v17, v215
	v_mul_f32_e32 v17, v131, v17
	v_fma_f32 v17, v139, v17, v135
	v_cndmask_b32_e32 v140, v49, v53, vcc
	v_cndmask_b32_e32 v144, v17, v21, vcc
	s_nop 0
	v_mov_b32_dpp v141, v140 quad_perm:[1,0,3,2] row_mask:0xf bank_mask:0xf
	v_mov_b32_dpp v145, v144 quad_perm:[1,0,3,2] row_mask:0xf bank_mask:0xf
	s_nop 0
	v_cndmask_b32_e32 v142, v53, v141, vcc
	v_cndmask_b32_e32 v143, v141, v49, vcc
	v_cndmask_b32_e32 v146, v21, v145, vcc
	v_cndmask_b32_e32 v147, v145, v17, vcc
	v_cvt_pk_bf16_f32 v150, v142, v143
	global_store_dword v177, v150, s[34:35]
	v_cvt_pk_bf16_f32 v151, v146, v147
	global_store_dword v177, v151, s[34:35] offset:256
	v_mul_f32_e32 v54, v54, v216
	v_mul_f32_e32 v54, v128, v54
	v_fma_f32 v54, v136, v54, v132
	v_mul_f32_e32 v50, v50, v216
	v_mul_f32_e32 v50, v129, v50
	v_fma_f32 v50, v137, v50, v133
	v_mul_f32_e32 v22, v22, v216
	v_mul_f32_e32 v22, v130, v22
	v_fma_f32 v22, v138, v22, v134
	v_mul_f32_e32 v18, v18, v216
	v_mul_f32_e32 v18, v131, v18
	v_fma_f32 v18, v139, v18, v135
	v_cndmask_b32_e32 v140, v50, v54, vcc
	v_cndmask_b32_e32 v144, v18, v22, vcc
	s_nop 0
	v_mov_b32_dpp v141, v140 quad_perm:[1,0,3,2] row_mask:0xf bank_mask:0xf
	v_mov_b32_dpp v145, v144 quad_perm:[1,0,3,2] row_mask:0xf bank_mask:0xf
	s_nop 0
	v_cndmask_b32_e32 v142, v54, v141, vcc
	v_cndmask_b32_e32 v143, v141, v50, vcc
	v_cndmask_b32_e32 v146, v22, v145, vcc
	v_cndmask_b32_e32 v147, v145, v18, vcc
	v_cvt_pk_bf16_f32 v152, v142, v143
	global_store_dword v178, v152, s[34:35]
	v_cvt_pk_bf16_f32 v153, v146, v147
	global_store_dword v178, v153, s[34:35] offset:256
	v_mul_f32_e32 v55, v55, v217
	v_mul_f32_e32 v55, v128, v55
	v_fma_f32 v55, v136, v55, v132
	v_mul_f32_e32 v51, v51, v217
	v_mul_f32_e32 v51, v129, v51
	v_fma_f32 v51, v137, v51, v133
	v_mul_f32_e32 v23, v23, v217
	v_mul_f32_e32 v23, v130, v23
	v_fma_f32 v23, v138, v23, v134
	v_mul_f32_e32 v19, v19, v217
	v_mul_f32_e32 v19, v131, v19
	v_fma_f32 v19, v139, v19, v135
	v_cndmask_b32_e32 v140, v51, v55, vcc
	v_cndmask_b32_e32 v144, v19, v23, vcc
	s_nop 0
	v_mov_b32_dpp v141, v140 quad_perm:[1,0,3,2] row_mask:0xf bank_mask:0xf
	v_mov_b32_dpp v145, v144 quad_perm:[1,0,3,2] row_mask:0xf bank_mask:0xf
	s_nop 0
	v_cndmask_b32_e32 v142, v55, v141, vcc
	v_cndmask_b32_e32 v143, v141, v51, vcc
	v_cndmask_b32_e32 v146, v23, v145, vcc
	v_cndmask_b32_e32 v147, v145, v19, vcc
	v_cvt_pk_bf16_f32 v154, v142, v143
	global_store_dword v179, v154, s[34:35]
	v_cvt_pk_bf16_f32 v155, v146, v147
	global_store_dword v179, v155, s[34:35] offset:256
	v_add_u32_e32 v176, 0xa0000, v172
	v_add_u32_e32 v177, 0xa0000, v173
	v_add_u32_e32 v178, 0xa0000, v174
	v_add_u32_e32 v179, 0xa0000, v175
	v_mul_f32_e32 v44, v44, v218
	v_mul_f32_e32 v44, v128, v44
	v_fma_f32 v44, v136, v44, v132
	v_mul_f32_e32 v40, v40, v218
	v_mul_f32_e32 v40, v129, v40
	v_fma_f32 v40, v137, v40, v133
	v_mul_f32_e32 v12, v12, v218
	v_mul_f32_e32 v12, v130, v12
	v_fma_f32 v12, v138, v12, v134
	v_mul_f32_e32 v8, v8, v218
	v_mul_f32_e32 v8, v131, v8
	v_fma_f32 v8, v139, v8, v135
	v_cndmask_b32_e32 v140, v40, v44, vcc
	v_cndmask_b32_e32 v144, v8, v12, vcc
	s_nop 0
	v_mov_b32_dpp v141, v140 quad_perm:[1,0,3,2] row_mask:0xf bank_mask:0xf
	v_mov_b32_dpp v145, v144 quad_perm:[1,0,3,2] row_mask:0xf bank_mask:0xf
	s_nop 0
	v_cndmask_b32_e32 v142, v44, v141, vcc
	v_cndmask_b32_e32 v143, v141, v40, vcc
	v_cndmask_b32_e32 v146, v12, v145, vcc
	v_cndmask_b32_e32 v147, v145, v8, vcc
	v_cvt_pk_bf16_f32 v148, v142, v143
	global_store_dword v176, v148, s[34:35]
	v_cvt_pk_bf16_f32 v149, v146, v147
	global_store_dword v176, v149, s[34:35] offset:256
	v_mul_f32_e32 v45, v45, v219
	v_mul_f32_e32 v45, v128, v45
	v_fma_f32 v45, v136, v45, v132
	v_mul_f32_e32 v41, v41, v219
	v_mul_f32_e32 v41, v129, v41
	v_fma_f32 v41, v137, v41, v133
	v_mul_f32_e32 v13, v13, v219
	v_mul_f32_e32 v13, v130, v13
	v_fma_f32 v13, v138, v13, v134
	v_mul_f32_e32 v9, v9, v219
	v_mul_f32_e32 v9, v131, v9
	v_fma_f32 v9, v139, v9, v135
	v_cndmask_b32_e32 v140, v41, v45, vcc
	v_cndmask_b32_e32 v144, v9, v13, vcc
	s_nop 0
	v_mov_b32_dpp v141, v140 quad_perm:[1,0,3,2] row_mask:0xf bank_mask:0xf
	v_mov_b32_dpp v145, v144 quad_perm:[1,0,3,2] row_mask:0xf bank_mask:0xf
	s_nop 0
	v_cndmask_b32_e32 v142, v45, v141, vcc
	v_cndmask_b32_e32 v143, v141, v41, vcc
	v_cndmask_b32_e32 v146, v13, v145, vcc
	v_cndmask_b32_e32 v147, v145, v9, vcc
	v_cvt_pk_bf16_f32 v150, v142, v143
	global_store_dword v177, v150, s[34:35]
	v_cvt_pk_bf16_f32 v151, v146, v147
	global_store_dword v177, v151, s[34:35] offset:256
	v_mul_f32_e32 v46, v46, v220
	v_mul_f32_e32 v46, v128, v46
	v_fma_f32 v46, v136, v46, v132
	v_mul_f32_e32 v42, v42, v220
	v_mul_f32_e32 v42, v129, v42
	v_fma_f32 v42, v137, v42, v133
	v_mul_f32_e32 v14, v14, v220
	v_mul_f32_e32 v14, v130, v14
	v_fma_f32 v14, v138, v14, v134
	v_mul_f32_e32 v10, v10, v220
	v_mul_f32_e32 v10, v131, v10
	v_fma_f32 v10, v139, v10, v135
	v_cndmask_b32_e32 v140, v42, v46, vcc
	v_cndmask_b32_e32 v144, v10, v14, vcc
	s_nop 0
	v_mov_b32_dpp v141, v140 quad_perm:[1,0,3,2] row_mask:0xf bank_mask:0xf
	v_mov_b32_dpp v145, v144 quad_perm:[1,0,3,2] row_mask:0xf bank_mask:0xf
	s_nop 0
	v_cndmask_b32_e32 v142, v46, v141, vcc
	v_cndmask_b32_e32 v143, v141, v42, vcc
	v_cndmask_b32_e32 v146, v14, v145, vcc
	v_cndmask_b32_e32 v147, v145, v10, vcc
	v_cvt_pk_bf16_f32 v152, v142, v143
	global_store_dword v178, v152, s[34:35]
	v_cvt_pk_bf16_f32 v153, v146, v147
	global_store_dword v178, v153, s[34:35] offset:256
	v_mul_f32_e32 v47, v47, v221
	v_mul_f32_e32 v47, v128, v47
	v_fma_f32 v47, v136, v47, v132
	v_mul_f32_e32 v43, v43, v221
	v_mul_f32_e32 v43, v129, v43
	v_fma_f32 v43, v137, v43, v133
	v_mul_f32_e32 v15, v15, v221
	v_mul_f32_e32 v15, v130, v15
	v_fma_f32 v15, v138, v15, v134
	v_mul_f32_e32 v11, v11, v221
	v_mul_f32_e32 v11, v131, v11
	v_fma_f32 v11, v139, v11, v135
	v_cndmask_b32_e32 v140, v43, v47, vcc
	v_cndmask_b32_e32 v144, v11, v15, vcc
	s_nop 0
	v_mov_b32_dpp v141, v140 quad_perm:[1,0,3,2] row_mask:0xf bank_mask:0xf
	v_mov_b32_dpp v145, v144 quad_perm:[1,0,3,2] row_mask:0xf bank_mask:0xf
	s_nop 0
	v_cndmask_b32_e32 v142, v47, v141, vcc
	v_cndmask_b32_e32 v143, v141, v43, vcc
	v_cndmask_b32_e32 v146, v15, v145, vcc
	v_cndmask_b32_e32 v147, v145, v11, vcc
	v_cvt_pk_bf16_f32 v154, v142, v143
	global_store_dword v179, v154, s[34:35]
	v_cvt_pk_bf16_f32 v155, v146, v147
	global_store_dword v179, v155, s[34:35] offset:256
	v_add_u32_e32 v176, 0xb0000, v172
	v_add_u32_e32 v177, 0xb0000, v173
	v_add_u32_e32 v178, 0xb0000, v174
	v_add_u32_e32 v179, 0xb0000, v175
	v_mul_f32_e32 v36, v36, v222
	v_mul_f32_e32 v36, v128, v36
	v_fma_f32 v36, v136, v36, v132
	v_mul_f32_e32 v28, v28, v222
	v_mul_f32_e32 v28, v129, v28
	v_fma_f32 v28, v137, v28, v133
	v_mul_f32_e32 v4, v4, v222
	v_mul_f32_e32 v4, v130, v4
	v_fma_f32 v4, v138, v4, v134
	v_mul_f32_e32 v0, v0, v222
	v_mul_f32_e32 v0, v131, v0
	v_fma_f32 v0, v139, v0, v135
	v_cndmask_b32_e32 v140, v28, v36, vcc
	v_cndmask_b32_e32 v144, v0, v4, vcc
	s_nop 0
	v_mov_b32_dpp v141, v140 quad_perm:[1,0,3,2] row_mask:0xf bank_mask:0xf
	v_mov_b32_dpp v145, v144 quad_perm:[1,0,3,2] row_mask:0xf bank_mask:0xf
	s_nop 0
	v_cndmask_b32_e32 v142, v36, v141, vcc
	v_cndmask_b32_e32 v143, v141, v28, vcc
	v_cndmask_b32_e32 v146, v4, v145, vcc
	v_cndmask_b32_e32 v147, v145, v0, vcc
	v_cvt_pk_bf16_f32 v148, v142, v143
	global_store_dword v176, v148, s[34:35]
	v_cvt_pk_bf16_f32 v149, v146, v147
	global_store_dword v176, v149, s[34:35] offset:256
	v_mul_f32_e32 v37, v37, v223
	v_mul_f32_e32 v37, v128, v37
	v_fma_f32 v37, v136, v37, v132
	v_mul_f32_e32 v29, v29, v223
	v_mul_f32_e32 v29, v129, v29
	v_fma_f32 v29, v137, v29, v133
	v_mul_f32_e32 v5, v5, v223
	v_mul_f32_e32 v5, v130, v5
	v_fma_f32 v5, v138, v5, v134
	v_mul_f32_e32 v1, v1, v223
	v_mul_f32_e32 v1, v131, v1
	v_fma_f32 v1, v139, v1, v135
	v_cndmask_b32_e32 v140, v29, v37, vcc
	v_cndmask_b32_e32 v144, v1, v5, vcc
	s_nop 0
	v_mov_b32_dpp v141, v140 quad_perm:[1,0,3,2] row_mask:0xf bank_mask:0xf
	v_mov_b32_dpp v145, v144 quad_perm:[1,0,3,2] row_mask:0xf bank_mask:0xf
	s_nop 0
	v_cndmask_b32_e32 v142, v37, v141, vcc
	v_cndmask_b32_e32 v143, v141, v29, vcc
	v_cndmask_b32_e32 v146, v5, v145, vcc
	v_cndmask_b32_e32 v147, v145, v1, vcc
	v_cvt_pk_bf16_f32 v150, v142, v143
	global_store_dword v177, v150, s[34:35]
	v_cvt_pk_bf16_f32 v151, v146, v147
	global_store_dword v177, v151, s[34:35] offset:256
	v_mul_f32_e32 v38, v38, v224
	v_mul_f32_e32 v38, v128, v38
	v_fma_f32 v38, v136, v38, v132
	v_mul_f32_e32 v30, v30, v224
	v_mul_f32_e32 v30, v129, v30
	v_fma_f32 v30, v137, v30, v133
	v_mul_f32_e32 v6, v6, v224
	v_mul_f32_e32 v6, v130, v6
	v_fma_f32 v6, v138, v6, v134
	v_mul_f32_e32 v2, v2, v224
	v_mul_f32_e32 v2, v131, v2
	v_fma_f32 v2, v139, v2, v135
	v_cndmask_b32_e32 v140, v30, v38, vcc
	v_cndmask_b32_e32 v144, v2, v6, vcc
	s_nop 0
	v_mov_b32_dpp v141, v140 quad_perm:[1,0,3,2] row_mask:0xf bank_mask:0xf
	v_mov_b32_dpp v145, v144 quad_perm:[1,0,3,2] row_mask:0xf bank_mask:0xf
	s_nop 0
	v_cndmask_b32_e32 v142, v38, v141, vcc
	v_cndmask_b32_e32 v143, v141, v30, vcc
	v_cndmask_b32_e32 v146, v6, v145, vcc
	v_cndmask_b32_e32 v147, v145, v2, vcc
	v_cvt_pk_bf16_f32 v152, v142, v143
	global_store_dword v178, v152, s[34:35]
	v_cvt_pk_bf16_f32 v153, v146, v147
	global_store_dword v178, v153, s[34:35] offset:256
	v_mul_f32_e32 v39, v39, v225
	v_mul_f32_e32 v39, v128, v39
	v_fma_f32 v39, v136, v39, v132
	v_mul_f32_e32 v31, v31, v225
	v_mul_f32_e32 v31, v129, v31
	v_fma_f32 v31, v137, v31, v133
	v_mul_f32_e32 v7, v7, v225
	v_mul_f32_e32 v7, v130, v7
	v_fma_f32 v7, v138, v7, v134
	v_mul_f32_e32 v3, v3, v225
	v_mul_f32_e32 v3, v131, v3
	v_fma_f32 v3, v139, v3, v135
	v_cndmask_b32_e32 v140, v31, v39, vcc
	v_cndmask_b32_e32 v144, v3, v7, vcc
	s_nop 0
	v_mov_b32_dpp v141, v140 quad_perm:[1,0,3,2] row_mask:0xf bank_mask:0xf
	v_mov_b32_dpp v145, v144 quad_perm:[1,0,3,2] row_mask:0xf bank_mask:0xf
	s_nop 0
	v_cndmask_b32_e32 v142, v39, v141, vcc
	v_cndmask_b32_e32 v143, v141, v31, vcc
	v_cndmask_b32_e32 v146, v7, v145, vcc
	v_cndmask_b32_e32 v147, v145, v3, vcc
	v_cvt_pk_bf16_f32 v154, v142, v143
	global_store_dword v179, v154, s[34:35]
	v_cvt_pk_bf16_f32 v155, v146, v147
	global_store_dword v179, v155, s[34:35] offset:256
.Lgo_p2_end:
	v_readlane_b32 s0, v254, 1
	s_add_i32 s44, s44, s0
	s_barrier
	v_readlane_b32 s1, v254, 2
	s_cmp_ge_i32 s44, s46
	s_cbranch_scc1 .LBB0_1172

.Lpost_nopre:
	s_cmp_eq_u32 s40, 0
	s_cselect_b32 s9, s44, 0
	s_lshl_b32 s9, s9, 14
	s_add_u32 s16, s16, s9
	s_movk_i32 s9, 0x4000
	s_cmp_eq_u32 s40, 0
	s_cselect_b32 s9, 0x4400, s9
	s_cmp_lt_u32 s16, s9
	s_cbranch_scc0 .Lpost_done
